# RG-LRU: the two unit-top workgroup barriers are kept only on the first-unit path (weight staging); later units have no cross-wave LDS dependency there (static weight image, per-sub-block summary slots
# speedup vs baseline: 1.0010x; 1.0010x over previous
.LBB0_245:
	v_mov_b32_e32 v90, v177
	s_andn2_b64 vcc, exec, s[4:5]
	v_readfirstlane_b32 s20, v90
	s_waitcnt vmcnt(4)
	v_lshlrev_b32_e32 v8, 4, v90
	s_cbranch_vccnz .LBB0_264
	s_barrier
	s_waitcnt vmcnt(0)
	v_mul_f32_e32 v149, 0xbfb8aa3b, v149
	v_exp_f32_e32 v149, v149
	s_nop 0
	v_add_f32_e32 v152, 1.0, v149
	v_add_f32_e32 v153, -1.0, v152
	v_frexp_mant_f32_e32 v154, v152
	v_cvt_f64_f32_e32 v[16:17], v152
	v_sub_f32_e32 v155, v153, v152
	v_frexp_exp_i32_f64_e32 v16, v[16:17]
	v_cmp_gt_f32_e32 vcc, s88, v154
	v_sub_f32_e32 v153, v149, v153
	v_add_f32_e32 v150, 1.0, v155
	v_subbrev_co_u32_e32 v16, vcc, 0, v16, vcc
	v_add_f32_e32 v150, v153, v150
	v_sub_u32_e32 v153, 0, v16
	v_cvt_f32_i32_e32 v16, v16
	v_ldexp_f32 v152, v152, v153
	v_ldexp_f32 v150, v150, v153
	v_add_f32_e32 v153, -1.0, v152
	v_add_f32_e32 v154, 1.0, v152
	v_add_f32_e32 v155, 1.0, v153
	v_add_f32_e32 v156, -1.0, v154
	v_sub_f32_e32 v155, v152, v155
	v_sub_f32_e32 v152, v152, v156
	v_mul_f32_e32 v156, 0x3f317218, v16
	v_add_f32_e32 v155, v150, v155
	v_add_f32_e32 v150, v150, v152
	v_fma_f32 v152, v16, s89, -v156
	v_add_f32_e32 v157, v153, v155
	v_add_f32_e32 v158, v154, v150
	v_fmac_f32_e32 v152, 0xb102e308, v16
	v_sub_f32_e32 v16, v157, v153
	v_sub_f32_e32 v153, v158, v154
	v_rcp_f32_e32 v154, v158
	v_add_f32_e32 v159, v156, v152
	v_sub_f32_e32 v150, v150, v153
	v_sub_f32_e32 v153, v159, v156
	v_sub_f32_e32 v152, v152, v153
	v_mul_f32_e32 v153, v157, v154
	v_sub_f32_e32 v16, v155, v16
	v_mul_f32_e32 v155, v158, v153
	v_fma_f32 v156, v153, v158, -v155
	v_fmac_f32_e32 v156, v153, v150
	v_add_f32_e32 v160, v155, v156
	v_sub_f32_e32 v161, v157, v160
	v_sub_f32_e32 v155, v160, v155
	v_sub_f32_e32 v157, v157, v161
	v_sub_f32_e32 v155, v155, v156
	v_sub_f32_e32 v156, v157, v160
	v_add_f32_e32 v16, v16, v156
	v_add_f32_e32 v16, v155, v16
	v_add_f32_e32 v155, v161, v16
	v_mul_f32_e32 v156, v154, v155
	v_sub_f32_e32 v157, v161, v155
	v_mul_f32_e32 v160, v158, v156
	v_add_f32_e32 v16, v16, v157
	v_add_f32_e32 v157, v153, v156
	v_fma_f32 v158, v156, v158, -v160
	v_sub_f32_e32 v153, v157, v153
	v_fmac_f32_e32 v158, v156, v150
	v_sub_f32_e32 v150, v156, v153
	v_add_f32_e32 v153, v160, v158
	v_sub_f32_e32 v156, v153, v160
	v_sub_f32_e32 v160, v155, v153
	v_sub_f32_e32 v155, v155, v160
	v_sub_f32_e32 v153, v155, v153
	v_sub_f32_e32 v156, v156, v158
	v_add_f32_e32 v16, v16, v153
	v_add_f32_e32 v16, v156, v16
	v_add_f32_e32 v16, v160, v16
	v_mul_f32_e32 v16, v154, v16
	v_add_f32_e32 v16, v150, v16
	v_add_f32_e32 v150, v157, v16
	v_mul_f32_e32 v153, v150, v150
	v_fmamk_f32 v156, v153, 0x3e9b6dac, v127
	v_sub_f32_e32 v154, v150, v157
	v_ldexp_f32 v155, v150, 1
	v_mul_f32_e32 v150, v150, v153
	v_fmaak_f32 v153, v153, v156, 0x3f2aaada
	v_mul_f32_e32 v150, v150, v153
	v_add_f32_e32 v153, v155, v150
	v_sub_f32_e32 v16, v16, v154
	v_sub_f32_e32 v154, v153, v155
	v_ldexp_f32 v16, v16, 1
	v_sub_f32_e32 v150, v150, v154
	v_add_f32_e32 v16, v16, v150
	v_add_f32_e32 v150, v153, v16
	v_sub_f32_e32 v153, v150, v153
	v_add_f32_e32 v154, v159, v150
	v_sub_f32_e32 v16, v16, v153
	v_sub_f32_e32 v153, v154, v159
	v_sub_f32_e32 v155, v154, v153
	v_sub_f32_e32 v150, v150, v153
	v_add_f32_e32 v153, v152, v16
	v_sub_f32_e32 v155, v159, v155
	v_sub_f32_e32 v156, v153, v152
	v_add_f32_e32 v150, v150, v155
	v_sub_f32_e32 v155, v153, v156
	v_sub_f32_e32 v16, v16, v156
	v_sub_f32_e32 v152, v152, v155
	v_add_f32_e32 v150, v153, v150
	v_add_f32_e32 v16, v16, v152
	v_add_f32_e32 v152, v154, v150
	v_sub_f32_e32 v153, v152, v154
	v_sub_f32_e32 v150, v150, v153
	v_add_f32_e32 v16, v16, v150
	v_add_f32_e32 v16, v152, v16
	v_cmp_neq_f32_e32 vcc, s90, v149
	v_cndmask_b32_e32 v16, v130, v16, vcc
	v_cmp_ngt_f32_e32 vcc, -1.0, v149
	v_cndmask_b32_e32 v16, v131, v16, vcc
	v_cmp_neq_f32_e32 vcc, -1.0, v149
	v_cndmask_b32_e32 v16, v132, v16, vcc
	v_cmp_lt_f32_e64 vcc, |v149|, s91
	v_cndmask_b32_e32 v16, v16, v149, vcc
	v_mul_f32_e32 v149, 0xc1000000, v16
	ds_write_b32 v136, v149
	v_and_b32_e32 v238, 0x7f, v177
	v_lshrrev_b32_e32 v239, 7, v177
	v_or_b32_e32 v238, s73, v238
	v_lshl_or_b32 v238, v239, 10, v238
	v_lshlrev_b32_e32 v238, 2, v238
	global_load_dword v240, v238, s[26:27]
	v_or_b32_e32 v239, s73, v177
	v_lshlrev_b32_e32 v239, 2, v239
	v_cmp_gt_u32_e32 vcc, 0x80, v177
	s_and_saveexec_b64 s[100:101], vcc
	global_load_dword v241, v239, s[28:29]
	s_mov_b64 exec, s[100:101]
	v_add_u32_e32 v91, 0x200, v90
	v_add_u32_e32 v10, 0x400, v90
	v_add_u32_e32 v12, 0x600, v90
	v_add_u32_e32 v18, 0x800, v90
	v_add_u32_e32 v20, 0xa00, v90
	v_add_u32_e32 v28, 0xc00, v90
	v_add_u32_e32 v30, 0xe00, v90
	v_ashrrev_i32_e32 v9, 4, v90
	s_waitcnt vmcnt(3)
	v_ashrrev_i32_e32 v34, 4, v91
	v_ashrrev_i32_e32 v35, 4, v10
	v_ashrrev_i32_e32 v36, 4, v12
	v_ashrrev_i32_e32 v37, 4, v18
	v_ashrrev_i32_e32 v38, 4, v20
	v_ashrrev_i32_e32 v39, 4, v28
	v_ashrrev_i32_e32 v40, 4, v30
	v_and_b32_e32 v88, 0xf0, v8
	v_lshlrev_b32_e32 v0, 7, v9
	v_lshlrev_b32_e32 v2, 7, v34
	v_lshlrev_b32_e32 v10, 7, v35
	v_lshlrev_b32_e32 v12, 7, v36
	v_lshlrev_b32_e32 v18, 7, v37
	v_lshlrev_b32_e32 v20, 7, v38
	v_lshlrev_b32_e32 v28, 7, v39
	v_lshlrev_b32_e32 v30, 7, v40
	v_lshl_add_u64 v[26:27], s[22:23], 0, v[88:89]
	v_ashrrev_i32_e32 v1, 31, v0
	v_ashrrev_i32_e32 v3, 31, v2
	v_ashrrev_i32_e32 v11, 31, v10
	v_ashrrev_i32_e32 v13, 31, v12
	v_ashrrev_i32_e32 v19, 31, v18
	v_ashrrev_i32_e32 v21, 31, v20
	v_ashrrev_i32_e32 v29, 31, v28
	v_ashrrev_i32_e32 v31, 31, v30
	v_lshl_add_u64 v[0:1], v[0:1], 1, v[26:27]
	v_lshl_add_u64 v[4:5], v[2:3], 1, v[26:27]
	v_lshl_add_u64 v[10:11], v[10:11], 1, v[26:27]
	v_lshl_add_u64 v[14:15], v[12:13], 1, v[26:27]
	v_lshl_add_u64 v[18:19], v[18:19], 1, v[26:27]
	v_lshl_add_u64 v[22:23], v[20:21], 1, v[26:27]
	v_lshl_add_u64 v[28:29], v[28:29], 1, v[26:27]
	v_lshl_add_u64 v[30:31], v[30:31], 1, v[26:27]
	global_load_dwordx4 v[0:3], v[0:1], off
	s_nop 0
	global_load_dwordx4 v[4:7], v[4:5], off
	s_nop 0
	global_load_dwordx4 v[10:13], v[10:11], off
	s_nop 0
	global_load_dwordx4 v[14:17], v[14:15], off
	s_nop 0
	global_load_dwordx4 v[18:21], v[18:19], off
	s_nop 0
	global_load_dwordx4 v[22:25], v[22:23], off
	s_nop 0
	global_load_dwordx4 v[26:29], v[28:29], off
	s_nop 0
	global_load_dwordx4 v[30:33], v[30:31], off
	v_and_b32_e32 v41, 0x70, v90
	v_xad_u32 v41, v88, v41, 16
	v_lshl_add_u32 v9, v9, 8, v41
	v_cmp_gt_i32_e32 vcc, s79, v90
	v_lshl_add_u32 v34, v34, 8, v41
	v_lshl_add_u32 v35, v35, 8, v41
	v_lshl_add_u32 v36, v36, 8, v41
	v_lshl_add_u32 v37, v37, 8, v41
	v_lshl_add_u32 v38, v38, 8, v41
	v_lshl_add_u32 v39, v39, 8, v41
	v_lshl_add_u32 v40, v40, 8, v41
	s_waitcnt vmcnt(7)
	ds_write_b128 v9, v[0:3] offset:16384
	s_waitcnt vmcnt(6)
	ds_write_b128 v34, v[4:7] offset:16384
	s_waitcnt vmcnt(5)
	ds_write_b128 v35, v[10:13] offset:16384
	s_waitcnt vmcnt(4)
	ds_write_b128 v36, v[14:17] offset:16384
	s_waitcnt vmcnt(3)
	ds_write_b128 v37, v[18:21] offset:16384
	s_waitcnt vmcnt(2)
	ds_write_b128 v38, v[22:25] offset:16384
	s_waitcnt vmcnt(1)
	ds_write_b128 v39, v[26:29] offset:16384
	s_waitcnt vmcnt(0)
	ds_write_b128 v40, v[30:33] offset:16384
	v_lshl_add_u32 v238, v177, 2, s82
	ds_write_b32 v238, v240
	v_cmp_gt_u32_e32 vcc, 0x80, v177
	s_and_saveexec_b64 s[100:101], vcc
	ds_write_b32 v238, v241 offset:2048
	s_mov_b64 exec, s[100:101]

.LBB0_264:
	s_and_b32 s65, s96, 63
	s_ashr_i32 s64, s20, 6
	s_lshl_b32 s4, s65, 8
	s_lshl_b32 s5, s64, 5
	v_and_b32_e32 v93, 31, v90
	s_add_i32 s12, s5, s4
	v_or_b32_e32 v9, s12, v93
	v_add_u32_e32 v0, -2, v9
	v_cmp_gt_u32_e32 vcc, s84, v0
	v_bfe_u32 v92, v90, 5, 1
	s_lshl_b32 s20, s73, 1
	v_cndmask_b32_e32 v2, v9, v0, vcc
	v_mov_b64_e32 v[0:1], s[52:53]
	v_mad_i64_i32 v[2:3], s[4:5], v2, s85, v[0:1]
	v_lshl_add_u64 v[2:3], v[2:3], 0, s[20:21]
	v_lshlrev_b32_e32 v88, 4, v92
	v_lshl_add_u64 v[4:5], v[2:3], 0, v[88:89]
	v_add_co_u32_e64 v2, s[4:5], s86, v4
	s_waitcnt lgkmcnt(0)
	s_nop 0
	v_addc_co_u32_e64 v3, s[4:5], 0, v5, s[4:5]
	global_load_dwordx4 v[10:13], v[2:3], off offset:1024
	global_load_dwordx4 v[178:181], v[2:3], off offset:1056
	global_load_dwordx4 v[194:197], v[2:3], off offset:1088
	global_load_dwordx4 v[210:213], v[2:3], off offset:1120
	global_load_dwordx4 v[226:229], v[2:3], off offset:1152
	global_load_dwordx4 v[242:245], v[2:3], off offset:1184
	v_add_u32_e32 v2, -1, v9
	v_cmp_gt_u32_e64 s[4:5], s84, v2
	v_add_u32_e32 v18, 1, v9
	s_cmpk_lt_u32 s12, 0x4000
	v_cndmask_b32_e64 v2, v9, v2, s[4:5]
	v_mad_i64_i32 v[2:3], s[6:7], v2, s85, v[0:1]
	v_lshl_add_u64 v[2:3], v[2:3], 0, s[20:21]
	v_lshl_add_u64 v[2:3], v[2:3], 0, v[88:89]
	v_add_co_u32_e64 v6, s[6:7], s86, v2
	v_lshlrev_b32_e32 v91, 8, v93
	s_nop 0
	v_addc_co_u32_e64 v7, s[6:7], 0, v3, s[6:7]
	global_load_dwordx4 v[14:17], v[6:7], off offset:1024
	global_load_dwordx4 v[182:185], v[6:7], off offset:1056
	global_load_dwordx4 v[198:201], v[6:7], off offset:1088
	global_load_dwordx4 v[214:217], v[6:7], off offset:1120
	global_load_dwordx4 v[230:233], v[6:7], off offset:1152
	global_load_dwordx4 v[246:249], v[6:7], off offset:1184
	v_mad_i64_i32 v[6:7], s[6:7], v9, s85, v[0:1]
	v_cmp_gt_u32_e64 s[6:7], s84, v18
	v_lshl_add_u64 v[6:7], v[6:7], 0, s[20:21]
	v_lshl_add_u64 v[52:53], v[6:7], 0, v[88:89]
	v_cndmask_b32_e64 v9, v9, v18, s[6:7]
	v_mad_i64_i32 v[0:1], s[8:9], v9, s85, v[0:1]
	v_add_co_u32_e64 v6, s[8:9], s86, v52
	v_lshl_add_u64 v[0:1], v[0:1], 0, s[20:21]
	s_nop 0
	v_addc_co_u32_e64 v7, s[8:9], 0, v53, s[8:9]
	global_load_dwordx4 v[18:21], v[6:7], off offset:1024
	global_load_dwordx4 v[186:189], v[6:7], off offset:1056
	global_load_dwordx4 v[202:205], v[6:7], off offset:1088
	global_load_dwordx4 v[218:221], v[6:7], off offset:1120
	global_load_dwordx4 v[234:237], v[6:7], off offset:1152
	global_load_dwordx4 v[252:255], v[6:7], off offset:1184
	v_lshl_add_u64 v[6:7], v[0:1], 0, v[88:89]
	v_add_co_u32_e64 v0, s[8:9], s86, v6
	v_lshl_add_u32 v9, v92, 5, 16
	s_nop 0
	v_addc_co_u32_e64 v1, s[8:9], 0, v7, s[8:9]
	global_load_dwordx4 v[22:25], v[0:1], off offset:1024
	global_load_dwordx4 v[190:193], v[0:1], off offset:1056
	global_load_dwordx4 v[206:209], v[0:1], off offset:1088
	global_load_dwordx4 v[222:225], v[0:1], off offset:1120
	global_load_dwordx4 v[238:241], v[0:1], off offset:1152
	global_load_dwordx4 v[168:171], v[0:1], off offset:1184
	s_waitcnt vmcnt(26)
	s_waitcnt lgkmcnt(4)
	v_lshl_add_u64 v[0:1], v[4:5], 0, s[38:39]
	s_cselect_b64 s[8:9], -1, 0
	v_lshl_add_u64 v[6:7], v[6:7], 0, s[38:39]
	v_or_b32_e32 v138, s73, v93
	v_and_b32_e32 v8, 0x70, v8
	v_add_u32_e32 v94, 16, v91
	s_waitcnt vmcnt(23)
	s_waitcnt vmcnt(17)
	s_waitcnt lgkmcnt(3)
	s_waitcnt lgkmcnt(1)
	s_waitcnt lgkmcnt(0)
	s_waitcnt vmcnt(11)
	s_waitcnt vmcnt(5)
	ds_read_b128 v[26:29], v9 offset:10240
	ds_read_b128 v[30:33], v9 offset:10256
	ds_read_b128 v[34:37], v9 offset:8192
	ds_read_b128 v[38:41], v9 offset:8208
	ds_read_b128 v[42:45], v9 offset:8704
	ds_read_b128 v[80:83], v9 offset:8720
	s_mov_b64 exec, vcc
	v_lshlrev_b32_e32 v4, 16, v10
	v_and_b32_e32 v5, 0xffff0000, v10
	v_lshlrev_b32_e32 v46, 16, v11
	v_and_b32_e32 v47, 0xffff0000, v11
	s_waitcnt lgkmcnt(2)
	v_pk_fma_f32 v[26:27], v[34:35], v[4:5], v[26:27]
	v_pk_fma_f32 v[28:29], v[36:37], v[46:47], v[28:29]
	v_lshlrev_b32_e32 v84, 16, v12
	v_and_b32_e32 v85, 0xffff0000, v12
	v_lshlrev_b32_e32 v86, 16, v13
	v_and_b32_e32 v87, 0xffff0000, v13
	v_pk_fma_f32 v[30:31], v[38:39], v[84:85], v[30:31]
	v_pk_fma_f32 v[32:33], v[40:41], v[86:87], v[32:33]
	s_mov_b64 exec, -1
	ds_read_b128 v[34:37], v9 offset:9216
	ds_read_b128 v[38:41], v9 offset:9232
	s_mov_b64 exec, s[4:5]
	v_lshlrev_b32_e32 v4, 16, v14
	v_and_b32_e32 v5, 0xffff0000, v14
	v_lshlrev_b32_e32 v46, 16, v15
	v_and_b32_e32 v47, 0xffff0000, v15
	s_waitcnt lgkmcnt(2)
	v_pk_fma_f32 v[26:27], v[42:43], v[4:5], v[26:27]
	v_pk_fma_f32 v[28:29], v[44:45], v[46:47], v[28:29]
	v_lshlrev_b32_e32 v84, 16, v16
	v_and_b32_e32 v85, 0xffff0000, v16
	v_lshlrev_b32_e32 v86, 16, v17
	v_and_b32_e32 v87, 0xffff0000, v17
	v_pk_fma_f32 v[30:31], v[80:81], v[84:85], v[30:31]
	v_pk_fma_f32 v[32:33], v[82:83], v[86:87], v[32:33]
	s_mov_b64 exec, -1
	ds_read_b128 v[42:45], v9 offset:9728
	ds_read_b128 v[80:83], v9 offset:9744
	v_lshlrev_b32_e32 v4, 16, v18
	v_and_b32_e32 v5, 0xffff0000, v18
	v_lshlrev_b32_e32 v46, 16, v19
	v_and_b32_e32 v47, 0xffff0000, v19
	s_waitcnt lgkmcnt(2)
	v_pk_fma_f32 v[26:27], v[34:35], v[4:5], v[26:27]
	v_pk_fma_f32 v[28:29], v[36:37], v[46:47], v[28:29]
	v_lshlrev_b32_e32 v84, 16, v20
	v_and_b32_e32 v85, 0xffff0000, v20
	v_lshlrev_b32_e32 v86, 16, v21
	v_and_b32_e32 v87, 0xffff0000, v21
	v_pk_fma_f32 v[30:31], v[38:39], v[84:85], v[30:31]
	v_pk_fma_f32 v[32:33], v[40:41], v[86:87], v[32:33]
	s_mov_b64 exec, s[6:7]
	v_lshlrev_b32_e32 v4, 16, v22
	v_and_b32_e32 v5, 0xffff0000, v22
	v_lshlrev_b32_e32 v46, 16, v23
	v_and_b32_e32 v47, 0xffff0000, v23
	s_waitcnt lgkmcnt(0)
	v_pk_fma_f32 v[26:27], v[42:43], v[4:5], v[26:27]
	v_pk_fma_f32 v[28:29], v[44:45], v[46:47], v[28:29]
	v_lshlrev_b32_e32 v84, 16, v24
	v_and_b32_e32 v85, 0xffff0000, v24
	v_lshlrev_b32_e32 v86, 16, v25
	v_and_b32_e32 v87, 0xffff0000, v25
	v_pk_fma_f32 v[30:31], v[80:81], v[84:85], v[30:31]
	v_pk_fma_f32 v[32:33], v[82:83], v[86:87], v[32:33]
	s_mov_b64 exec, -1
	v_cvt_pk_bf16_f32 v48, v26, v27
	v_cvt_pk_bf16_f32 v49, v28, v29
	v_cvt_pk_bf16_f32 v50, v30, v31
	v_cvt_pk_bf16_f32 v51, v32, v33
	s_waitcnt lgkmcnt(3)
	s_waitcnt lgkmcnt(1)
	s_waitcnt lgkmcnt(0)
	s_nop 0
	v_lshl_add_u64 v[4:5], v[2:3], 0, s[38:39]
	v_lshl_add_u64 v[2:3], v[52:53], 0, s[38:39]
	s_waitcnt vmcnt(4)
	s_waitcnt vmcnt(4)
	s_waitcnt lgkmcnt(3)
	s_waitcnt lgkmcnt(1)
	s_waitcnt lgkmcnt(0)
	s_waitcnt vmcnt(4)
	ds_read_b128 v[26:29], v9 offset:10304
	ds_read_b128 v[30:33], v9 offset:10320
	ds_read_b128 v[34:37], v9 offset:8256
	ds_read_b128 v[38:41], v9 offset:8272
	ds_read_b128 v[42:45], v9 offset:8768
	ds_read_b128 v[80:83], v9 offset:8784
	s_mov_b64 exec, vcc
	v_lshlrev_b32_e32 v46, 16, v178
	v_and_b32_e32 v47, 0xffff0000, v178
	v_lshlrev_b32_e32 v84, 16, v179
	v_and_b32_e32 v85, 0xffff0000, v179
	s_waitcnt lgkmcnt(2)
	v_pk_fma_f32 v[26:27], v[34:35], v[46:47], v[26:27]
	v_pk_fma_f32 v[28:29], v[36:37], v[84:85], v[28:29]
	v_lshlrev_b32_e32 v86, 16, v180
	v_and_b32_e32 v87, 0xffff0000, v180
	v_lshlrev_b32_e32 v96, 16, v181
	v_and_b32_e32 v97, 0xffff0000, v181
	v_pk_fma_f32 v[30:31], v[38:39], v[86:87], v[30:31]
	v_pk_fma_f32 v[32:33], v[40:41], v[96:97], v[32:33]
	s_mov_b64 exec, -1
	ds_read_b128 v[34:37], v9 offset:9280
	ds_read_b128 v[38:41], v9 offset:9296
	s_mov_b64 exec, s[4:5]
	v_lshlrev_b32_e32 v46, 16, v182
	v_and_b32_e32 v47, 0xffff0000, v182
	v_lshlrev_b32_e32 v84, 16, v183
	v_and_b32_e32 v85, 0xffff0000, v183
	s_waitcnt lgkmcnt(2)
	v_pk_fma_f32 v[26:27], v[42:43], v[46:47], v[26:27]
	v_pk_fma_f32 v[28:29], v[44:45], v[84:85], v[28:29]
	v_lshlrev_b32_e32 v86, 16, v184
	v_and_b32_e32 v87, 0xffff0000, v184
	v_lshlrev_b32_e32 v96, 16, v185
	v_and_b32_e32 v97, 0xffff0000, v185
	v_pk_fma_f32 v[30:31], v[80:81], v[86:87], v[30:31]
	v_pk_fma_f32 v[32:33], v[82:83], v[96:97], v[32:33]
	s_mov_b64 exec, -1
	ds_read_b128 v[42:45], v9 offset:9792
	ds_read_b128 v[80:83], v9 offset:9808
	v_lshlrev_b32_e32 v46, 16, v186
	v_and_b32_e32 v47, 0xffff0000, v186
	v_lshlrev_b32_e32 v84, 16, v187
	v_and_b32_e32 v85, 0xffff0000, v187
	s_waitcnt lgkmcnt(2)
	v_pk_fma_f32 v[26:27], v[34:35], v[46:47], v[26:27]
	v_pk_fma_f32 v[28:29], v[36:37], v[84:85], v[28:29]
	v_lshlrev_b32_e32 v86, 16, v188
	v_and_b32_e32 v87, 0xffff0000, v188
	v_lshlrev_b32_e32 v96, 16, v189
	v_and_b32_e32 v97, 0xffff0000, v189
	v_pk_fma_f32 v[30:31], v[38:39], v[86:87], v[30:31]
	v_pk_fma_f32 v[32:33], v[40:41], v[96:97], v[32:33]
	s_mov_b64 exec, s[6:7]
	v_lshlrev_b32_e32 v46, 16, v190
	v_and_b32_e32 v47, 0xffff0000, v190
	v_lshlrev_b32_e32 v84, 16, v191
	v_and_b32_e32 v85, 0xffff0000, v191
	s_waitcnt lgkmcnt(0)
	v_pk_fma_f32 v[26:27], v[42:43], v[46:47], v[26:27]
	v_pk_fma_f32 v[28:29], v[44:45], v[84:85], v[28:29]
	v_lshlrev_b32_e32 v86, 16, v192
	v_and_b32_e32 v87, 0xffff0000, v192
	v_lshlrev_b32_e32 v96, 16, v193
	v_and_b32_e32 v97, 0xffff0000, v193
	v_pk_fma_f32 v[30:31], v[80:81], v[86:87], v[30:31]
	v_pk_fma_f32 v[32:33], v[82:83], v[96:97], v[32:33]
	s_mov_b64 exec, -1
	v_cvt_pk_bf16_f32 v52, v26, v27
	v_cvt_pk_bf16_f32 v53, v28, v29
	v_cvt_pk_bf16_f32 v54, v30, v31
	v_cvt_pk_bf16_f32 v55, v32, v33
	s_waitcnt lgkmcnt(3)
	s_waitcnt lgkmcnt(1)
	s_waitcnt lgkmcnt(0)
	s_nop 0
	global_load_dwordx4 v[178:181], v[0:1], off offset:192
	global_load_dwordx4 v[182:185], v[4:5], off offset:192
	global_load_dwordx4 v[186:189], v[2:3], off offset:192
	global_load_dwordx4 v[190:193], v[6:7], off offset:192
	s_waitcnt vmcnt(7)
	s_waitcnt vmcnt(7)
	s_waitcnt lgkmcnt(3)
	s_waitcnt lgkmcnt(1)
	s_waitcnt lgkmcnt(0)
	s_waitcnt vmcnt(7)
	s_waitcnt vmcnt(7)
	ds_read_b128 v[26:29], v9 offset:10368
	ds_read_b128 v[30:33], v9 offset:10384
	ds_read_b128 v[34:37], v9 offset:8320
	ds_read_b128 v[38:41], v9 offset:8336
	ds_read_b128 v[42:45], v9 offset:8832
	ds_read_b128 v[80:83], v9 offset:8848
	s_mov_b64 exec, vcc
	v_lshlrev_b32_e32 v46, 16, v194
	v_and_b32_e32 v47, 0xffff0000, v194
	v_lshlrev_b32_e32 v84, 16, v195
	v_and_b32_e32 v85, 0xffff0000, v195
	s_waitcnt lgkmcnt(2)
	v_pk_fma_f32 v[26:27], v[34:35], v[46:47], v[26:27]
	v_pk_fma_f32 v[28:29], v[36:37], v[84:85], v[28:29]
	v_lshlrev_b32_e32 v86, 16, v196
	v_and_b32_e32 v87, 0xffff0000, v196
	v_lshlrev_b32_e32 v96, 16, v197
	v_and_b32_e32 v97, 0xffff0000, v197
	v_pk_fma_f32 v[30:31], v[38:39], v[86:87], v[30:31]
	v_pk_fma_f32 v[32:33], v[40:41], v[96:97], v[32:33]
	s_mov_b64 exec, -1
	ds_read_b128 v[34:37], v9 offset:9344
	ds_read_b128 v[38:41], v9 offset:9360
	s_mov_b64 exec, s[4:5]
	v_lshlrev_b32_e32 v46, 16, v198
	v_and_b32_e32 v47, 0xffff0000, v198
	v_lshlrev_b32_e32 v84, 16, v199
	v_and_b32_e32 v85, 0xffff0000, v199
	s_waitcnt lgkmcnt(2)
	v_pk_fma_f32 v[26:27], v[42:43], v[46:47], v[26:27]
	v_pk_fma_f32 v[28:29], v[44:45], v[84:85], v[28:29]
	v_lshlrev_b32_e32 v86, 16, v200
	v_and_b32_e32 v87, 0xffff0000, v200
	v_lshlrev_b32_e32 v96, 16, v201
	v_and_b32_e32 v97, 0xffff0000, v201
	v_pk_fma_f32 v[30:31], v[80:81], v[86:87], v[30:31]
	v_pk_fma_f32 v[32:33], v[82:83], v[96:97], v[32:33]
	s_mov_b64 exec, -1
	ds_read_b128 v[42:45], v9 offset:9856
	ds_read_b128 v[80:83], v9 offset:9872
	v_lshlrev_b32_e32 v46, 16, v202
	v_and_b32_e32 v47, 0xffff0000, v202
	v_lshlrev_b32_e32 v84, 16, v203
	v_and_b32_e32 v85, 0xffff0000, v203
	s_waitcnt lgkmcnt(2)
	v_pk_fma_f32 v[26:27], v[34:35], v[46:47], v[26:27]
	v_pk_fma_f32 v[28:29], v[36:37], v[84:85], v[28:29]
	v_lshlrev_b32_e32 v86, 16, v204
	v_and_b32_e32 v87, 0xffff0000, v204
	v_lshlrev_b32_e32 v96, 16, v205
	v_and_b32_e32 v97, 0xffff0000, v205
	v_pk_fma_f32 v[30:31], v[38:39], v[86:87], v[30:31]
	v_pk_fma_f32 v[32:33], v[40:41], v[96:97], v[32:33]
	s_mov_b64 exec, s[6:7]
	v_lshlrev_b32_e32 v46, 16, v206
	v_and_b32_e32 v47, 0xffff0000, v206
	v_lshlrev_b32_e32 v84, 16, v207
	v_and_b32_e32 v85, 0xffff0000, v207
	s_waitcnt lgkmcnt(0)
	v_pk_fma_f32 v[26:27], v[42:43], v[46:47], v[26:27]
	v_pk_fma_f32 v[28:29], v[44:45], v[84:85], v[28:29]
	v_lshlrev_b32_e32 v86, 16, v208
	v_and_b32_e32 v87, 0xffff0000, v208
	v_lshlrev_b32_e32 v96, 16, v209
	v_and_b32_e32 v97, 0xffff0000, v209
	v_pk_fma_f32 v[30:31], v[80:81], v[86:87], v[30:31]
	v_pk_fma_f32 v[32:33], v[82:83], v[96:97], v[32:33]
	s_mov_b64 exec, -1
	v_cvt_pk_bf16_f32 v56, v26, v27
	v_cvt_pk_bf16_f32 v57, v28, v29
	v_cvt_pk_bf16_f32 v58, v30, v31
	v_cvt_pk_bf16_f32 v59, v32, v33
	s_waitcnt lgkmcnt(3)
	s_waitcnt lgkmcnt(1)
	s_waitcnt lgkmcnt(0)
	s_nop 0
	global_load_dwordx4 v[194:197], v[0:1], off offset:224
	global_load_dwordx4 v[198:201], v[4:5], off offset:224
	global_load_dwordx4 v[202:205], v[2:3], off offset:224
	global_load_dwordx4 v[206:209], v[6:7], off offset:224
	s_waitcnt vmcnt(10)
	s_waitcnt vmcnt(10)
	s_waitcnt lgkmcnt(3)
	s_waitcnt lgkmcnt(1)
	s_waitcnt lgkmcnt(0)
	s_waitcnt vmcnt(10)
	s_waitcnt vmcnt(10)
	ds_read_b128 v[0:3], v9 offset:10432
	ds_read_b128 v[4:7], v9 offset:10448
	ds_read_b128 v[26:29], v9 offset:8384
	ds_read_b128 v[30:33], v9 offset:8400
	ds_read_b128 v[34:37], v9 offset:8896
	ds_read_b128 v[38:41], v9 offset:8912
	s_mov_b64 exec, vcc
	v_lshlrev_b32_e32 v42, 16, v210
	v_and_b32_e32 v43, 0xffff0000, v210
	v_lshlrev_b32_e32 v44, 16, v211
	v_and_b32_e32 v45, 0xffff0000, v211
	s_waitcnt lgkmcnt(2)
	v_pk_fma_f32 v[0:1], v[26:27], v[42:43], v[0:1]
	v_pk_fma_f32 v[2:3], v[28:29], v[44:45], v[2:3]
	v_lshlrev_b32_e32 v46, 16, v212
	v_and_b32_e32 v47, 0xffff0000, v212
	v_lshlrev_b32_e32 v80, 16, v213
	v_and_b32_e32 v81, 0xffff0000, v213
	v_pk_fma_f32 v[4:5], v[30:31], v[46:47], v[4:5]
	v_pk_fma_f32 v[6:7], v[32:33], v[80:81], v[6:7]
	s_mov_b64 exec, -1
	ds_read_b128 v[26:29], v9 offset:9408
	ds_read_b128 v[30:33], v9 offset:9424
	s_mov_b64 exec, s[4:5]
	v_lshlrev_b32_e32 v42, 16, v214
	v_and_b32_e32 v43, 0xffff0000, v214
	v_lshlrev_b32_e32 v44, 16, v215
	v_and_b32_e32 v45, 0xffff0000, v215
	s_waitcnt lgkmcnt(2)
	v_pk_fma_f32 v[0:1], v[34:35], v[42:43], v[0:1]
	v_pk_fma_f32 v[2:3], v[36:37], v[44:45], v[2:3]
	v_lshlrev_b32_e32 v46, 16, v216
	v_and_b32_e32 v47, 0xffff0000, v216
	v_lshlrev_b32_e32 v80, 16, v217
	v_and_b32_e32 v81, 0xffff0000, v217
	v_pk_fma_f32 v[4:5], v[38:39], v[46:47], v[4:5]
	v_pk_fma_f32 v[6:7], v[40:41], v[80:81], v[6:7]
	s_mov_b64 exec, -1
	ds_read_b128 v[34:37], v9 offset:9920
	ds_read_b128 v[38:41], v9 offset:9936
	v_lshlrev_b32_e32 v42, 16, v218
	v_and_b32_e32 v43, 0xffff0000, v218
	v_lshlrev_b32_e32 v44, 16, v219
	v_and_b32_e32 v45, 0xffff0000, v219
	s_waitcnt lgkmcnt(2)
	v_pk_fma_f32 v[0:1], v[26:27], v[42:43], v[0:1]
	v_pk_fma_f32 v[2:3], v[28:29], v[44:45], v[2:3]
	v_lshlrev_b32_e32 v46, 16, v220
	v_and_b32_e32 v47, 0xffff0000, v220
	v_lshlrev_b32_e32 v80, 16, v221
	v_and_b32_e32 v81, 0xffff0000, v221
	v_pk_fma_f32 v[4:5], v[30:31], v[46:47], v[4:5]
	v_pk_fma_f32 v[6:7], v[32:33], v[80:81], v[6:7]
	s_mov_b64 exec, s[6:7]
	v_lshlrev_b32_e32 v42, 16, v222
	v_and_b32_e32 v43, 0xffff0000, v222
	v_lshlrev_b32_e32 v44, 16, v223
	v_and_b32_e32 v45, 0xffff0000, v223
	s_waitcnt lgkmcnt(0)
	v_pk_fma_f32 v[0:1], v[34:35], v[42:43], v[0:1]
	v_pk_fma_f32 v[2:3], v[36:37], v[44:45], v[2:3]
	v_lshlrev_b32_e32 v46, 16, v224
	v_and_b32_e32 v47, 0xffff0000, v224
	v_lshlrev_b32_e32 v80, 16, v225
	v_and_b32_e32 v81, 0xffff0000, v225
	v_pk_fma_f32 v[4:5], v[38:39], v[46:47], v[4:5]
	v_pk_fma_f32 v[6:7], v[40:41], v[80:81], v[6:7]
	s_mov_b64 exec, -1
	v_cvt_pk_bf16_f32 v60, v0, v1
	v_cvt_pk_bf16_f32 v61, v2, v3
	v_cvt_pk_bf16_f32 v62, v4, v5
	v_cvt_pk_bf16_f32 v63, v6, v7
	s_waitcnt lgkmcnt(3)
	s_waitcnt lgkmcnt(1)
	s_waitcnt lgkmcnt(0)
	s_nop 0
	s_waitcnt vmcnt(9)
	s_waitcnt vmcnt(9)
	s_waitcnt lgkmcnt(3)
	s_waitcnt lgkmcnt(1)
	s_waitcnt lgkmcnt(0)
	s_waitcnt vmcnt(9)
	s_waitcnt vmcnt(9)
	ds_read_b128 v[0:3], v9 offset:10496
	ds_read_b128 v[4:7], v9 offset:10512
	ds_read_b128 v[26:29], v9 offset:8448
	ds_read_b128 v[30:33], v9 offset:8464
	ds_read_b128 v[34:37], v9 offset:8960
	ds_read_b128 v[38:41], v9 offset:8976
	s_mov_b64 exec, vcc
	v_lshlrev_b32_e32 v42, 16, v226
	v_and_b32_e32 v43, 0xffff0000, v226
	v_lshlrev_b32_e32 v44, 16, v227
	v_and_b32_e32 v45, 0xffff0000, v227
	s_waitcnt lgkmcnt(2)
	v_pk_fma_f32 v[0:1], v[26:27], v[42:43], v[0:1]
	v_pk_fma_f32 v[2:3], v[28:29], v[44:45], v[2:3]
	v_lshlrev_b32_e32 v46, 16, v228
	v_and_b32_e32 v47, 0xffff0000, v228
	v_lshlrev_b32_e32 v80, 16, v229
	v_and_b32_e32 v81, 0xffff0000, v229
	v_pk_fma_f32 v[4:5], v[30:31], v[46:47], v[4:5]
	v_pk_fma_f32 v[6:7], v[32:33], v[80:81], v[6:7]
	s_mov_b64 exec, -1
	ds_read_b128 v[26:29], v9 offset:9472
	ds_read_b128 v[30:33], v9 offset:9488
	s_mov_b64 exec, s[4:5]
	v_lshlrev_b32_e32 v42, 16, v230
	v_and_b32_e32 v43, 0xffff0000, v230
	v_lshlrev_b32_e32 v44, 16, v231
	v_and_b32_e32 v45, 0xffff0000, v231
	s_waitcnt lgkmcnt(2)
	v_pk_fma_f32 v[0:1], v[34:35], v[42:43], v[0:1]
	v_pk_fma_f32 v[2:3], v[36:37], v[44:45], v[2:3]
	v_lshlrev_b32_e32 v46, 16, v232
	v_and_b32_e32 v47, 0xffff0000, v232
	v_lshlrev_b32_e32 v80, 16, v233
	v_and_b32_e32 v81, 0xffff0000, v233
	v_pk_fma_f32 v[4:5], v[38:39], v[46:47], v[4:5]
	v_pk_fma_f32 v[6:7], v[40:41], v[80:81], v[6:7]
	s_mov_b64 exec, -1
	ds_read_b128 v[34:37], v9 offset:9984
	ds_read_b128 v[38:41], v9 offset:10000
	v_lshlrev_b32_e32 v42, 16, v234
	v_and_b32_e32 v43, 0xffff0000, v234
	v_lshlrev_b32_e32 v44, 16, v235
	v_and_b32_e32 v45, 0xffff0000, v235
	s_waitcnt lgkmcnt(2)
	v_pk_fma_f32 v[0:1], v[26:27], v[42:43], v[0:1]
	v_pk_fma_f32 v[2:3], v[28:29], v[44:45], v[2:3]
	v_lshlrev_b32_e32 v46, 16, v236
	v_and_b32_e32 v47, 0xffff0000, v236
	v_lshlrev_b32_e32 v80, 16, v237
	v_and_b32_e32 v81, 0xffff0000, v237
	v_pk_fma_f32 v[4:5], v[30:31], v[46:47], v[4:5]
	v_pk_fma_f32 v[6:7], v[32:33], v[80:81], v[6:7]
	s_mov_b64 exec, s[6:7]
	v_lshlrev_b32_e32 v42, 16, v238
	v_and_b32_e32 v43, 0xffff0000, v238
	v_lshlrev_b32_e32 v44, 16, v239
	v_and_b32_e32 v45, 0xffff0000, v239
	s_waitcnt lgkmcnt(0)
	v_pk_fma_f32 v[0:1], v[34:35], v[42:43], v[0:1]
	v_pk_fma_f32 v[2:3], v[36:37], v[44:45], v[2:3]
	v_lshlrev_b32_e32 v46, 16, v240
	v_and_b32_e32 v47, 0xffff0000, v240
	v_lshlrev_b32_e32 v80, 16, v241
	v_and_b32_e32 v81, 0xffff0000, v241
	v_pk_fma_f32 v[4:5], v[38:39], v[46:47], v[4:5]
	v_pk_fma_f32 v[6:7], v[40:41], v[80:81], v[6:7]
	s_mov_b64 exec, -1
	v_cvt_pk_bf16_f32 v64, v0, v1
	v_cvt_pk_bf16_f32 v65, v2, v3
	v_cvt_pk_bf16_f32 v66, v4, v5
	v_cvt_pk_bf16_f32 v67, v6, v7
	s_waitcnt lgkmcnt(3)
	s_waitcnt lgkmcnt(1)
	s_waitcnt lgkmcnt(0)
	s_nop 0
	s_waitcnt vmcnt(8)
	s_waitcnt vmcnt(8)
	s_waitcnt lgkmcnt(3)
	s_waitcnt lgkmcnt(1)
	s_waitcnt lgkmcnt(0)
	s_waitcnt vmcnt(8)
	s_waitcnt vmcnt(8)
	ds_read_b128 v[0:3], v9 offset:10560
	ds_read_b128 v[4:7], v9 offset:10576
	ds_read_b128 v[26:29], v9 offset:8512
	ds_read_b128 v[30:33], v9 offset:8528
	ds_read_b128 v[34:37], v9 offset:9024
	ds_read_b128 v[38:41], v9 offset:9040
	s_mov_b64 exec, vcc
	v_lshlrev_b32_e32 v42, 16, v242
	v_and_b32_e32 v43, 0xffff0000, v242
	v_lshlrev_b32_e32 v44, 16, v243
	v_and_b32_e32 v45, 0xffff0000, v243
	s_waitcnt lgkmcnt(2)
	v_pk_fma_f32 v[0:1], v[26:27], v[42:43], v[0:1]
	v_pk_fma_f32 v[2:3], v[28:29], v[44:45], v[2:3]
	v_lshlrev_b32_e32 v46, 16, v244
	v_and_b32_e32 v47, 0xffff0000, v244
	v_lshlrev_b32_e32 v80, 16, v245
	v_and_b32_e32 v81, 0xffff0000, v245
	v_pk_fma_f32 v[4:5], v[30:31], v[46:47], v[4:5]
	v_pk_fma_f32 v[6:7], v[32:33], v[80:81], v[6:7]
	s_mov_b64 exec, -1
	ds_read_b128 v[26:29], v9 offset:9536
	ds_read_b128 v[30:33], v9 offset:9552
	s_mov_b64 exec, s[4:5]
	v_lshlrev_b32_e32 v42, 16, v246
	v_and_b32_e32 v43, 0xffff0000, v246
	v_lshlrev_b32_e32 v44, 16, v247
	v_and_b32_e32 v45, 0xffff0000, v247
	s_waitcnt lgkmcnt(2)
	v_pk_fma_f32 v[0:1], v[34:35], v[42:43], v[0:1]
	v_pk_fma_f32 v[2:3], v[36:37], v[44:45], v[2:3]
	v_lshlrev_b32_e32 v46, 16, v248
	v_and_b32_e32 v47, 0xffff0000, v248
	v_lshlrev_b32_e32 v80, 16, v249
	v_and_b32_e32 v81, 0xffff0000, v249
	v_pk_fma_f32 v[4:5], v[38:39], v[46:47], v[4:5]
	v_pk_fma_f32 v[6:7], v[40:41], v[80:81], v[6:7]
	s_mov_b64 exec, -1
	ds_read_b128 v[34:37], v9 offset:10048
	ds_read_b128 v[38:41], v9 offset:10064
	v_lshlrev_b32_e32 v42, 16, v252
	v_and_b32_e32 v43, 0xffff0000, v252
	v_lshlrev_b32_e32 v44, 16, v253
	v_and_b32_e32 v45, 0xffff0000, v253
	s_waitcnt lgkmcnt(2)
	v_pk_fma_f32 v[0:1], v[26:27], v[42:43], v[0:1]
	v_pk_fma_f32 v[2:3], v[28:29], v[44:45], v[2:3]
	v_lshlrev_b32_e32 v46, 16, v254
	v_and_b32_e32 v47, 0xffff0000, v254
	v_lshlrev_b32_e32 v80, 16, v255
	v_and_b32_e32 v81, 0xffff0000, v255
	v_pk_fma_f32 v[4:5], v[30:31], v[46:47], v[4:5]
	v_pk_fma_f32 v[6:7], v[32:33], v[80:81], v[6:7]
	s_mov_b64 exec, s[6:7]
	v_lshlrev_b32_e32 v42, 16, v168
	v_and_b32_e32 v43, 0xffff0000, v168
	v_lshlrev_b32_e32 v44, 16, v169
	v_and_b32_e32 v45, 0xffff0000, v169
	s_waitcnt lgkmcnt(0)
	v_pk_fma_f32 v[0:1], v[34:35], v[42:43], v[0:1]
	v_pk_fma_f32 v[2:3], v[36:37], v[44:45], v[2:3]
	v_lshlrev_b32_e32 v46, 16, v170
	v_and_b32_e32 v47, 0xffff0000, v170
	v_lshlrev_b32_e32 v80, 16, v171
	v_and_b32_e32 v81, 0xffff0000, v171
	v_pk_fma_f32 v[4:5], v[38:39], v[46:47], v[4:5]
	v_pk_fma_f32 v[6:7], v[40:41], v[80:81], v[6:7]
	s_mov_b64 exec, -1
	v_cvt_pk_bf16_f32 v68, v0, v1
	v_cvt_pk_bf16_f32 v69, v2, v3
	v_cvt_pk_bf16_f32 v70, v4, v5
	v_cvt_pk_bf16_f32 v71, v6, v7
	s_waitcnt lgkmcnt(3)
	s_waitcnt lgkmcnt(1)
	s_waitcnt lgkmcnt(0)
	s_nop 0
	s_waitcnt vmcnt(4)
	s_waitcnt vmcnt(4)
	s_waitcnt lgkmcnt(3)
	s_waitcnt lgkmcnt(1)
	s_waitcnt lgkmcnt(0)
	s_waitcnt vmcnt(4)
	s_waitcnt vmcnt(4)
	ds_read_b128 v[0:3], v9 offset:10624
	ds_read_b128 v[4:7], v9 offset:10640
	ds_read_b128 v[26:29], v9 offset:8576
	ds_read_b128 v[30:33], v9 offset:8592
	ds_read_b128 v[34:37], v9 offset:9088
	ds_read_b128 v[38:41], v9 offset:9104
	s_mov_b64 exec, vcc
	v_lshlrev_b32_e32 v42, 16, v178
	v_and_b32_e32 v43, 0xffff0000, v178
	v_lshlrev_b32_e32 v44, 16, v179
	v_and_b32_e32 v45, 0xffff0000, v179
	s_waitcnt lgkmcnt(2)
	v_pk_fma_f32 v[0:1], v[26:27], v[42:43], v[0:1]
	v_pk_fma_f32 v[2:3], v[28:29], v[44:45], v[2:3]
	v_lshlrev_b32_e32 v46, 16, v180
	v_and_b32_e32 v47, 0xffff0000, v180
	v_lshlrev_b32_e32 v80, 16, v181
	v_and_b32_e32 v81, 0xffff0000, v181
	v_pk_fma_f32 v[4:5], v[30:31], v[46:47], v[4:5]
	v_pk_fma_f32 v[6:7], v[32:33], v[80:81], v[6:7]
	s_mov_b64 exec, -1
	ds_read_b128 v[26:29], v9 offset:9600
	ds_read_b128 v[30:33], v9 offset:9616
	s_mov_b64 exec, s[4:5]
	v_lshlrev_b32_e32 v42, 16, v182
	v_and_b32_e32 v43, 0xffff0000, v182
	v_lshlrev_b32_e32 v44, 16, v183
	v_and_b32_e32 v45, 0xffff0000, v183
	s_waitcnt lgkmcnt(2)
	v_pk_fma_f32 v[0:1], v[34:35], v[42:43], v[0:1]
	v_pk_fma_f32 v[2:3], v[36:37], v[44:45], v[2:3]
	v_lshlrev_b32_e32 v46, 16, v184
	v_and_b32_e32 v47, 0xffff0000, v184
	v_lshlrev_b32_e32 v80, 16, v185
	v_and_b32_e32 v81, 0xffff0000, v185
	v_pk_fma_f32 v[4:5], v[38:39], v[46:47], v[4:5]
	v_pk_fma_f32 v[6:7], v[40:41], v[80:81], v[6:7]
	s_mov_b64 exec, -1
	ds_read_b128 v[34:37], v9 offset:10112
	ds_read_b128 v[38:41], v9 offset:10128
	v_lshlrev_b32_e32 v42, 16, v186
	v_and_b32_e32 v43, 0xffff0000, v186
	v_lshlrev_b32_e32 v44, 16, v187
	v_and_b32_e32 v45, 0xffff0000, v187
	s_waitcnt lgkmcnt(2)
	v_pk_fma_f32 v[0:1], v[26:27], v[42:43], v[0:1]
	v_pk_fma_f32 v[2:3], v[28:29], v[44:45], v[2:3]
	v_lshlrev_b32_e32 v46, 16, v188
	v_and_b32_e32 v47, 0xffff0000, v188
	v_lshlrev_b32_e32 v80, 16, v189
	v_and_b32_e32 v81, 0xffff0000, v189
	v_pk_fma_f32 v[4:5], v[30:31], v[46:47], v[4:5]
	v_pk_fma_f32 v[6:7], v[32:33], v[80:81], v[6:7]
	s_mov_b64 exec, s[6:7]
	v_lshlrev_b32_e32 v42, 16, v190
	v_and_b32_e32 v43, 0xffff0000, v190
	v_lshlrev_b32_e32 v44, 16, v191
	v_and_b32_e32 v45, 0xffff0000, v191
	s_waitcnt lgkmcnt(0)
	v_pk_fma_f32 v[0:1], v[34:35], v[42:43], v[0:1]
	v_pk_fma_f32 v[2:3], v[36:37], v[44:45], v[2:3]
	v_lshlrev_b32_e32 v46, 16, v192
	v_and_b32_e32 v47, 0xffff0000, v192
	v_lshlrev_b32_e32 v80, 16, v193
	v_and_b32_e32 v81, 0xffff0000, v193
	v_pk_fma_f32 v[4:5], v[38:39], v[46:47], v[4:5]
	v_pk_fma_f32 v[6:7], v[40:41], v[80:81], v[6:7]
	s_mov_b64 exec, -1
	v_cvt_pk_bf16_f32 v72, v0, v1
	v_cvt_pk_bf16_f32 v73, v2, v3
	v_cvt_pk_bf16_f32 v74, v4, v5
	v_cvt_pk_bf16_f32 v75, v6, v7
	s_waitcnt lgkmcnt(3)
	s_waitcnt lgkmcnt(1)
	s_waitcnt lgkmcnt(0)
	v_lshlrev_b32_e32 v38, 3, v92
	s_nop 0
	s_nop 0
	v_or_b32_e32 v39, 16, v38
	s_waitcnt vmcnt(0)
	s_waitcnt vmcnt(0)
	s_waitcnt lgkmcnt(3)
	s_waitcnt lgkmcnt(1)
	s_waitcnt lgkmcnt(0)
	s_waitcnt vmcnt(0)
	s_waitcnt vmcnt(0)
	ds_read_b128 v[0:3], v9 offset:10688
	ds_read_b128 v[4:7], v9 offset:10704
	ds_read_b128 v[26:29], v9 offset:8640
	ds_read_b128 v[30:33], v9 offset:8656
	ds_read_b128 v[34:37], v9 offset:9152
	ds_read_b128 v[40:43], v9 offset:9168
	s_mov_b64 exec, vcc
	v_lshlrev_b32_e32 v44, 16, v194
	v_and_b32_e32 v45, 0xffff0000, v194
	v_lshlrev_b32_e32 v46, 16, v195
	v_and_b32_e32 v47, 0xffff0000, v195
	s_waitcnt lgkmcnt(2)
	v_pk_fma_f32 v[0:1], v[26:27], v[44:45], v[0:1]
	v_pk_fma_f32 v[2:3], v[28:29], v[46:47], v[2:3]
	v_lshlrev_b32_e32 v80, 16, v196
	v_and_b32_e32 v81, 0xffff0000, v196
	v_lshlrev_b32_e32 v82, 16, v197
	v_and_b32_e32 v83, 0xffff0000, v197
	v_pk_fma_f32 v[4:5], v[30:31], v[80:81], v[4:5]
	v_pk_fma_f32 v[6:7], v[32:33], v[82:83], v[6:7]
	s_mov_b64 exec, -1
	ds_read_b128 v[26:29], v9 offset:9664
	ds_read_b128 v[30:33], v9 offset:9680
	s_mov_b64 exec, s[4:5]
	v_lshlrev_b32_e32 v44, 16, v198
	v_and_b32_e32 v45, 0xffff0000, v198
	v_lshlrev_b32_e32 v46, 16, v199
	v_and_b32_e32 v47, 0xffff0000, v199
	s_waitcnt lgkmcnt(2)
	v_pk_fma_f32 v[0:1], v[34:35], v[44:45], v[0:1]
	v_pk_fma_f32 v[2:3], v[36:37], v[46:47], v[2:3]
	v_lshlrev_b32_e32 v80, 16, v200
	v_and_b32_e32 v81, 0xffff0000, v200
	v_lshlrev_b32_e32 v82, 16, v201
	v_and_b32_e32 v83, 0xffff0000, v201
	v_pk_fma_f32 v[4:5], v[40:41], v[80:81], v[4:5]
	v_pk_fma_f32 v[6:7], v[42:43], v[82:83], v[6:7]
	s_mov_b64 exec, -1
	ds_read_b128 v[34:37], v9 offset:10176
	ds_read_b128 v[40:43], v9 offset:10192
	v_lshlrev_b32_e32 v44, 16, v202
	v_and_b32_e32 v45, 0xffff0000, v202
	v_lshlrev_b32_e32 v46, 16, v203
	v_and_b32_e32 v47, 0xffff0000, v203
	s_waitcnt lgkmcnt(2)
	v_pk_fma_f32 v[0:1], v[26:27], v[44:45], v[0:1]
	v_pk_fma_f32 v[2:3], v[28:29], v[46:47], v[2:3]
	v_lshlrev_b32_e32 v80, 16, v204
	v_and_b32_e32 v81, 0xffff0000, v204
	v_lshlrev_b32_e32 v82, 16, v205
	v_and_b32_e32 v83, 0xffff0000, v205
	v_pk_fma_f32 v[4:5], v[30:31], v[80:81], v[4:5]
	v_pk_fma_f32 v[6:7], v[32:33], v[82:83], v[6:7]
	s_mov_b64 exec, s[6:7]
	v_lshlrev_b32_e32 v44, 16, v206
	v_and_b32_e32 v45, 0xffff0000, v206
	v_lshlrev_b32_e32 v46, 16, v207
	v_and_b32_e32 v47, 0xffff0000, v207
	s_waitcnt lgkmcnt(0)
	v_pk_fma_f32 v[0:1], v[34:35], v[44:45], v[0:1]
	v_pk_fma_f32 v[2:3], v[36:37], v[46:47], v[2:3]
	v_lshlrev_b32_e32 v80, 16, v208
	v_and_b32_e32 v81, 0xffff0000, v208
	v_lshlrev_b32_e32 v82, 16, v209
	v_and_b32_e32 v83, 0xffff0000, v209
	v_pk_fma_f32 v[4:5], v[40:41], v[80:81], v[4:5]
	v_pk_fma_f32 v[6:7], v[42:43], v[82:83], v[6:7]
	s_mov_b64 exec, -1
	v_cvt_pk_bf16_f32 v76, v0, v1
	v_cvt_pk_bf16_f32 v77, v2, v3
	v_cvt_pk_bf16_f32 v78, v4, v5
	v_cvt_pk_bf16_f32 v79, v6, v7
	s_waitcnt lgkmcnt(3)
	s_waitcnt lgkmcnt(1)
	s_waitcnt lgkmcnt(0)
	v_cmp_eq_u32_e32 vcc, v38, v93
	v_or_b32_e32 v2, 1, v38
	v_cndmask_b32_e32 v0, 0, v128, vcc
	v_or_b32_e32 v1, 2, v38
	v_cmp_eq_u32_e32 vcc, v2, v93
	v_or_b32_e32 v4, 3, v38
	v_or_b32_e32 v3, 4, v38
	v_cndmask_b32_e32 v2, 0, v128, vcc
	v_cmp_eq_u32_e32 vcc, v1, v93
	v_or_b32_e32 v5, 6, v38
	v_or_b32_e32 v6, 5, v38
	v_cndmask_b32_e32 v1, 0, v128, vcc
	v_cmp_eq_u32_e32 vcc, v4, v93
	v_or_b32_e32 v7, 7, v38
	v_or_b32_e32 v11, 17, v38
	v_cndmask_b32_e32 v4, 0, v128, vcc
	v_cmp_eq_u32_e32 vcc, v3, v93
	v_or_b32_e32 v10, 18, v38
	v_or_b32_e32 v13, 19, v38
	v_cndmask_b32_e32 v3, 0, v128, vcc
	v_cmp_eq_u32_e32 vcc, v5, v93
	v_or_b32_e32 v12, 20, v38
	v_or_b32_e32 v14, 22, v38
	v_cndmask_b32_e32 v5, 0, v128, vcc
	v_cmp_eq_u32_e32 vcc, v6, v93
	v_or_b32_e32 v15, 21, v38
	v_or_b32_e32 v16, 23, v38
	v_cndmask_b32_e32 v6, 0, v128, vcc
	v_cmp_eq_u32_e32 vcc, v7, v93
	v_and_b32_e32 v18, 64, v126
	v_xor_b32_e32 v17, 32, v126
	v_cndmask_b32_e32 v7, 0, v128, vcc
	v_cmp_eq_u32_e32 vcc, v39, v93
	v_add_u32_e32 v18, 64, v18
	s_lshl_b32 s6, s64, 8
	v_cndmask_b32_e32 v9, 0, v128, vcc
	v_cmp_eq_u32_e32 vcc, v11, v93
	s_add_i32 s6, s6, 16
	v_cmp_eq_u32_e64 s[4:5], 0, v92
	v_cndmask_b32_e32 v11, 0, v128, vcc
	v_cmp_eq_u32_e32 vcc, v10, v93
	v_lshl_add_u32 v136, v93, 3, s6
	v_perm_b32 v82, v6, v3, s87
	v_cndmask_b32_e32 v10, 0, v128, vcc
	v_cmp_eq_u32_e32 vcc, v13, v93
	v_perm_b32 v81, v4, v1, s87
	v_perm_b32 v83, v7, v5, s87
	v_cndmask_b32_e32 v13, 0, v128, vcc
	v_cmp_eq_u32_e32 vcc, v12, v93
	v_perm_b32 v80, v2, v0, s87
	v_perm_b32 v85, v13, v10, s87
	v_cndmask_b32_e32 v12, 0, v128, vcc
	v_cmp_eq_u32_e32 vcc, v14, v93
	v_perm_b32 v84, v11, v9, s87
	s_nop 0
	v_cndmask_b32_e32 v14, 0, v128, vcc
	v_cmp_eq_u32_e32 vcc, v15, v93
	s_nop 1
	v_cndmask_b32_e32 v15, 0, v128, vcc
	v_cmp_eq_u32_e32 vcc, v16, v93
	v_perm_b32 v86, v15, v12, s87
	s_nop 0
	v_cndmask_b32_e32 v16, 0, v128, vcc
	v_cmp_lt_i32_e32 vcc, v17, v18
	v_perm_b32 v87, v16, v14, s87
	s_nop 0
	v_cndmask_b32_e32 v17, v126, v17, vcc
	v_lshlrev_b32_e32 v137, 2, v17
	v_lshl_or_b32 v175, v138, 2, v129
	global_load_dword v172, v175, s[42:43]
	global_load_dword v173, v175, s[36:37]
	global_load_dword v174, v175, s[40:41]
	s_setprio 1
	v_xad_u32 v145, v88, v8, v94
	ds_read_b128 v[0:3], v145 offset:16384
	ds_read_b128 v[4:7], v145 offset:49152
	s_waitcnt lgkmcnt(1)
	v_mfma_f32_32x32x16_bf16 v[32:47], v[48:51], v[0:3], 0
	v_or_b32_e32 v0, 32, v88
	v_xad_u32 v147, v0, v8, v94
	s_waitcnt lgkmcnt(0)
	v_mfma_f32_32x32x16_bf16 v[16:31], v[48:51], v[4:7], 0
	ds_read_b128 v[0:3], v147 offset:16384
	ds_read_b128 v[4:7], v147 offset:49152
	s_waitcnt lgkmcnt(1)
	v_mfma_f32_32x32x16_bf16 v[32:47], v[52:55], v[0:3], v[32:47]
	v_or_b32_e32 v0, 64, v88
	v_xad_u32 v142, v0, v8, v94
	s_waitcnt lgkmcnt(0)
	v_mfma_f32_32x32x16_bf16 v[16:31], v[52:55], v[4:7], v[16:31]
	ds_read_b128 v[0:3], v142 offset:16384
	ds_read_b128 v[4:7], v142 offset:49152
	s_waitcnt lgkmcnt(1)
	v_mfma_f32_32x32x16_bf16 v[32:47], v[56:59], v[0:3], v[32:47]
	v_or_b32_e32 v0, 0x60, v88
	v_xad_u32 v146, v0, v8, v94
	s_waitcnt lgkmcnt(0)
	v_mfma_f32_32x32x16_bf16 v[16:31], v[56:59], v[4:7], v[16:31]
	ds_read_b128 v[0:3], v146 offset:16384
	ds_read_b128 v[4:7], v146 offset:49152
	s_waitcnt lgkmcnt(1)
	v_mfma_f32_32x32x16_bf16 v[32:47], v[60:63], v[0:3], v[32:47]
	v_or_b32_e32 v0, 0x80, v88
	v_xad_u32 v141, v0, v8, v94
	s_waitcnt lgkmcnt(0)
	v_mfma_f32_32x32x16_bf16 v[16:31], v[60:63], v[4:7], v[16:31]
	ds_read_b128 v[0:3], v141 offset:16384
	ds_read_b128 v[4:7], v141 offset:49152
	s_waitcnt lgkmcnt(1)
	v_mfma_f32_32x32x16_bf16 v[32:47], v[64:67], v[0:3], v[32:47]
	v_or_b32_e32 v0, 0xa0, v88
	v_xad_u32 v144, v0, v8, v94
	s_waitcnt lgkmcnt(0)
	v_mfma_f32_32x32x16_bf16 v[16:31], v[64:67], v[4:7], v[16:31]
	ds_read_b128 v[0:3], v144 offset:16384
	ds_read_b128 v[4:7], v144 offset:49152
	s_waitcnt lgkmcnt(1)
	v_mfma_f32_32x32x16_bf16 v[32:47], v[68:71], v[0:3], v[32:47]
	v_or_b32_e32 v0, 0xc0, v88
	v_xad_u32 v139, v0, v8, v94
	s_waitcnt lgkmcnt(0)
	v_mfma_f32_32x32x16_bf16 v[16:31], v[68:71], v[4:7], v[16:31]
	ds_read_b128 v[0:3], v139 offset:16384
	ds_read_b128 v[4:7], v139 offset:49152
	s_waitcnt lgkmcnt(1)
	v_mfma_f32_32x32x16_bf16 v[32:47], v[72:75], v[0:3], v[32:47]
	v_or_b32_e32 v0, 0xe0, v88
	v_xad_u32 v143, v0, v8, v94
	s_waitcnt lgkmcnt(0)
	v_mfma_f32_32x32x16_bf16 v[16:31], v[72:75], v[4:7], v[16:31]
	ds_read_b128 v[0:3], v143 offset:16384
	ds_read_b128 v[4:7], v143 offset:49152
	s_waitcnt lgkmcnt(1)
	v_mfma_f32_32x32x16_bf16 v[32:47], v[76:79], v[0:3], v[32:47]
	s_waitcnt lgkmcnt(0)
	v_mfma_f32_32x32x16_bf16 v[16:31], v[76:79], v[4:7], v[16:31]
	v_mfma_f32_32x32x16_bf16 v[0:15], v[48:51], v[80:83], 0
	v_mfma_f32_32x32x16_bf16 v[0:15], v[52:55], v[84:87], v[0:15]
	s_setprio 0
	v_lshl_or_b32 v88, v138, 2, v129
	s_waitcnt vmcnt(0)
	ds_read_b32 v251, v167
	v_mul_f32_e32 v94, 0xbfb8aa3b, v173
	v_mul_f32_e32 v88, 0xbfb8aa3b, v174
	v_fmamk_f32 v32, v32, 0xbfb8aa3b, v94
	v_fmamk_f32 v16, v16, 0xbfb8aa3b, v88
	v_exp_f32_e32 v32, v32
	v_exp_f32_e32 v96, v16
	v_fmamk_f32 v17, v17, 0xbfb8aa3b, v88
	v_exp_f32_e32 v97, v17
	v_add_f32_e32 v32, 1.0, v32
	v_add_f32_e32 v96, 1.0, v96
	v_rcp_f32_e32 v17, v32
	v_rcp_f32_e32 v32, v96
	v_fmamk_f32 v33, v33, 0xbfb8aa3b, v94
	v_fmamk_f32 v34, v34, 0xbfb8aa3b, v94
	v_exp_f32_e32 v33, v33
	v_exp_f32_e32 v34, v34
	v_add_f32_e32 v33, 1.0, v33
	v_add_f32_e32 v34, 1.0, v34
	v_rcp_f32_e32 v33, v33
	v_rcp_f32_e32 v34, v34
	v_fmamk_f32 v18, v18, 0xbfb8aa3b, v88
	v_fmamk_f32 v19, v19, 0xbfb8aa3b, v88
	v_exp_f32_e32 v18, v18
	s_waitcnt lgkmcnt(0)
	v_mul_f32_e32 v95, 0x3fb8aa3b, v251
	v_mul_f32_e32 v16, v17, v95
	v_mul_f32_e32 v17, v33, v95
	v_exp_f32_e32 v33, v16
	v_mul_f32_e32 v16, v34, v95
	v_exp_f32_e32 v98, v16
	v_fmamk_f32 v16, v35, 0xbfb8aa3b, v94
	v_exp_f32_e32 v16, v16
	v_exp_f32_e32 v96, v17
	v_add_f32_e32 v16, 1.0, v16
	v_rcp_f32_e32 v16, v16
	v_exp_f32_e32 v19, v19
	v_add_f32_e32 v97, 1.0, v97
	v_add_f32_e32 v18, 1.0, v18
	v_mul_f32_e32 v16, v16, v95
	v_exp_f32_e32 v16, v16
	v_fma_f32 v35, -v98, v98, 1.0
	v_rcp_f32_e32 v17, v97
	v_fma_f32 v34, -v33, v33, 1.0
	v_fma_f32 v97, -v96, v96, 1.0
	v_rcp_f32_e32 v18, v18
	v_sqrt_f32_e32 v35, v35
	v_add_f32_e32 v19, 1.0, v19
	v_fma_f32 v99, -v16, v16, 1.0
	v_sqrt_f32_e32 v34, v34
	v_sqrt_f32_e32 v97, v97
	v_rcp_f32_e32 v19, v19
	v_sqrt_f32_e32 v99, v99
	v_mul_f32_e32 v35, v18, v35
	v_fmamk_f32 v18, v36, 0xbfb8aa3b, v94
	v_mul_f32_e32 v32, v32, v34
	v_mul_f32_e32 v34, v17, v97
	v_mul_f32_e32 v17, v19, v99
	v_fmamk_f32 v19, v20, 0xbfb8aa3b, v88
	v_exp_f32_e32 v18, v18
	v_exp_f32_e32 v19, v19
	v_mul_f32_e32 v3, v3, v17
	v_add_f32_e32 v17, 1.0, v18
	v_rcp_f32_e32 v17, v17
	v_add_f32_e32 v18, 1.0, v19
	v_fmamk_f32 v19, v37, 0xbfb8aa3b, v94
	v_exp_f32_e32 v19, v19
	v_mul_f32_e32 v17, v17, v95
	v_exp_f32_e32 v36, v17
	v_add_f32_e32 v17, 1.0, v19
	v_rcp_f32_e32 v17, v17
	v_fmamk_f32 v19, v21, 0xbfb8aa3b, v88
	v_exp_f32_e32 v19, v19
	v_mul_f32_e32 v17, v17, v95
	v_exp_f32_e32 v37, v17
	v_fmamk_f32 v17, v38, 0xbfb8aa3b, v94
	v_exp_f32_e32 v17, v17
	v_fmamk_f32 v23, v23, 0xbfb8aa3b, v88
	v_add_f32_e32 v19, 1.0, v19
	v_fma_f32 v21, -v37, v37, 1.0
	v_add_f32_e32 v17, 1.0, v17
	v_rcp_f32_e32 v17, v17
	v_rcp_f32_e32 v19, v19
	v_sqrt_f32_e32 v21, v21
	v_mul_f32_e32 v17, v17, v95
	v_exp_f32_e32 v38, v17
	v_fmamk_f32 v17, v39, 0xbfb8aa3b, v94
	v_exp_f32_e32 v17, v17
	v_exp_f32_e32 v23, v23
	v_fma_f32 v20, -v36, v36, 1.0
	v_mul_f32_e32 v100, v19, v21
	v_add_f32_e32 v17, 1.0, v17
	v_rcp_f32_e32 v17, v17
	v_add_f32_e32 v23, 1.0, v23
	v_fmamk_f32 v19, v40, 0xbfb8aa3b, v94
	v_rcp_f32_e32 v18, v18
	v_mul_f32_e32 v17, v17, v95
	v_exp_f32_e32 v17, v17
	v_sqrt_f32_e32 v20, v20
	v_rcp_f32_e32 v23, v23
	v_fma_f32 v97, -v17, v17, 1.0
	v_sqrt_f32_e32 v97, v97
	v_fmamk_f32 v21, v24, 0xbfb8aa3b, v88
	v_fmamk_f32 v22, v22, 0xbfb8aa3b, v88
	v_exp_f32_e32 v19, v19
	v_exp_f32_e32 v21, v21
	v_exp_f32_e32 v22, v22
	v_mul_f32_e32 v99, v18, v20
	v_mul_f32_e32 v18, v23, v97
	v_mul_f32_e32 v7, v7, v18
	v_add_f32_e32 v18, 1.0, v19
	v_rcp_f32_e32 v18, v18
	v_add_f32_e32 v19, 1.0, v21
	v_fmamk_f32 v21, v41, 0xbfb8aa3b, v94
	v_add_f32_e32 v22, 1.0, v22
	v_fma_f32 v39, -v38, v38, 1.0
	v_rcp_f32_e32 v22, v22
	v_sqrt_f32_e32 v39, v39
	v_exp_f32_e32 v21, v21
	v_mul_f32_e32 v18, v18, v95
	v_mul_f32_e32 v20, v22, v39
	v_exp_f32_e32 v39, v18
	v_add_f32_e32 v18, 1.0, v21
	v_rcp_f32_e32 v18, v18
	v_fmamk_f32 v21, v25, 0xbfb8aa3b, v88
	v_exp_f32_e32 v21, v21
	v_mul_f32_e32 v18, v18, v95
	v_exp_f32_e32 v40, v18
	v_fmamk_f32 v18, v42, 0xbfb8aa3b, v94
	v_exp_f32_e32 v18, v18
	v_fmamk_f32 v24, v26, 0xbfb8aa3b, v88
	v_fmamk_f32 v26, v27, 0xbfb8aa3b, v88
	v_add_f32_e32 v21, 1.0, v21
	v_add_f32_e32 v18, 1.0, v18
	v_rcp_f32_e32 v18, v18
	v_fma_f32 v23, -v40, v40, 1.0
	v_fma_f32 v22, -v39, v39, 1.0
	v_mul_f32_e32 v18, v18, v95
	v_exp_f32_e32 v41, v18
	v_fmamk_f32 v18, v43, 0xbfb8aa3b, v94
	v_exp_f32_e32 v18, v18
	v_rcp_f32_e32 v21, v21
	v_sqrt_f32_e32 v23, v23
	v_exp_f32_e32 v26, v26
	v_add_f32_e32 v18, 1.0, v18
	v_rcp_f32_e32 v18, v18
	v_rcp_f32_e32 v19, v19
	v_sqrt_f32_e32 v22, v22
	v_add_f32_e32 v26, 1.0, v26
	v_mul_f32_e32 v18, v18, v95
	v_exp_f32_e32 v18, v18
	v_mul_f32_e32 v43, v21, v23
	v_fmamk_f32 v21, v44, 0xbfb8aa3b, v94
	v_rcp_f32_e32 v26, v26
	v_fma_f32 v27, -v18, v18, 1.0
	v_sqrt_f32_e32 v27, v27
	v_mul_f32_e32 v42, v19, v22
	v_fmamk_f32 v22, v28, 0xbfb8aa3b, v88
	v_exp_f32_e32 v21, v21
	v_exp_f32_e32 v22, v22
	v_mul_f32_e32 v19, v26, v27
	v_mul_f32_e32 v11, v11, v19
	v_add_f32_e32 v19, 1.0, v21
	v_rcp_f32_e32 v19, v19
	v_add_f32_e32 v21, 1.0, v22
	v_fmamk_f32 v22, v45, 0xbfb8aa3b, v94
	v_exp_f32_e32 v22, v22
	v_mul_f32_e32 v19, v19, v95
	v_exp_f32_e32 v44, v19
	v_add_f32_e32 v19, 1.0, v22
	v_rcp_f32_e32 v19, v19
	v_exp_f32_e32 v24, v24
	v_fma_f32 v25, -v41, v41, 1.0
	v_mul_f32_e32 v19, v19, v95
	v_exp_f32_e32 v45, v19
	v_fmamk_f32 v19, v46, 0xbfb8aa3b, v94
	v_exp_f32_e32 v19, v19
	v_add_f32_e32 v24, 1.0, v24
	v_rcp_f32_e32 v24, v24
	v_sqrt_f32_e32 v25, v25
	v_add_f32_e32 v19, 1.0, v19
	v_rcp_f32_e32 v19, v19
	v_fmamk_f32 v22, v29, 0xbfb8aa3b, v88
	v_mul_f32_e32 v97, v24, v25
	v_fma_f32 v24, -v45, v45, 1.0
	v_mul_f32_e32 v19, v19, v95
	v_exp_f32_e32 v46, v19
	v_fmamk_f32 v19, v47, 0xbfb8aa3b, v94
	v_exp_f32_e32 v19, v19
	v_sqrt_f32_e32 v25, v24
	v_fmamk_f32 v24, v30, 0xbfb8aa3b, v88
	v_exp_f32_e32 v24, v24
	v_add_f32_e32 v19, 1.0, v19
	v_rcp_f32_e32 v19, v19
	v_fma_f32 v27, -v46, v46, 1.0
	v_add_f32_e32 v24, 1.0, v24
	v_rcp_f32_e32 v26, v24
	v_fmamk_f32 v24, v31, 0xbfb8aa3b, v88
	v_mul_f32_e32 v19, v19, v95
	v_exp_f32_e32 v28, v24
	v_exp_f32_e32 v24, v19
	v_sqrt_f32_e32 v19, v27
	v_add_f32_e32 v27, 1.0, v28
	v_fma_f32 v28, -v24, v24, 1.0
	v_exp_f32_e32 v22, v22
	v_rcp_f32_e32 v27, v27
	v_sqrt_f32_e32 v28, v28
	v_fma_f32 v23, -v44, v44, 1.0
	v_rcp_f32_e32 v21, v21
	v_sqrt_f32_e32 v23, v23
	v_add_f32_e32 v22, 1.0, v22
	v_mul_f32_e32 v94, v26, v19
	v_mul_f32_e32 v19, v27, v28
	v_fmac_f32_e32 v7, 0, v17
	v_rcp_f32_e32 v22, v22
	v_mul_f32_e32 v15, v15, v19
	v_mul_f32_e32 v19, v38, v7
	v_fmac_f32_e32 v3, 0, v16
	v_fmac_f32_e32 v19, v6, v20
	v_mul_f32_e32 v47, v21, v23
	v_mul_f32_e32 v21, v98, v3
	v_mul_f32_e32 v20, v37, v19
	v_fmac_f32_e32 v15, 0, v24
	v_fmac_f32_e32 v21, v2, v35
	v_fmac_f32_e32 v20, v5, v100
	v_mul_f32_e32 v2, v46, v15
	v_mul_f32_e32 v88, v22, v25
	v_mul_f32_e32 v22, v36, v20
	v_fmac_f32_e32 v2, v14, v94
	v_fmac_f32_e32 v22, v4, v99
	v_mul_f32_e32 v4, v45, v2
	v_mul_f32_e32 v23, v96, v21
	v_fmac_f32_e32 v4, v13, v88
	v_fmac_f32_e32 v23, v1, v34
	v_fmac_f32_e32 v11, 0, v18
	v_mul_f32_e32 v14, v24, v46
	v_mul_f32_e32 v6, v44, v4
	v_mul_f32_e32 v25, v33, v23
	v_mul_f32_e32 v5, v41, v11
	v_mul_f32_e32 v13, v45, v14
	v_fmac_f32_e32 v6, v12, v47
	v_fmac_f32_e32 v25, v0, v32
	v_fmac_f32_e32 v5, v10, v97
	v_mul_f32_e32 v12, v44, v13
	ds_bpermute_b32 v0, v137, v6
	v_mul_f32_e32 v10, v40, v5
	ds_bpermute_b32 v35, v137, v12
	v_mul_f32_e32 v28, v18, v41
	v_fmac_f32_e32 v10, v9, v43
	v_mul_f32_e32 v26, v16, v98
	v_mul_f32_e32 v27, v17, v38
	v_mul_f32_e32 v31, v40, v28
	v_mul_f32_e32 v9, v39, v10
	v_mul_f32_e32 v29, v96, v26
	v_mul_f32_e32 v30, v37, v27
	v_fmac_f32_e32 v9, v8, v42
	v_mul_f32_e32 v34, v39, v31
	v_mul_f32_e32 v32, v33, v29
	v_mul_f32_e32 v33, v36, v30
	s_waitcnt lgkmcnt(1)
	v_cndmask_b32_e64 v36, v0, v6, s[4:5]
	v_cndmask_b32_e64 v37, v6, v0, s[4:5]
	ds_bpermute_b32 v0, v137, v34
	ds_bpermute_b32 v40, v137, v9
	s_waitcnt lgkmcnt(2)
	v_cndmask_b32_e64 v8, v12, v35, s[4:5]
	v_fmac_f32_e32 v37, 0, v8
	ds_bpermute_b32 v8, v137, v33
	v_cndmask_b32_e64 v1, v35, v12, s[4:5]
	v_mul_f32_e32 v38, v12, v35
	v_fmac_f32_e32 v36, v1, v37
	s_waitcnt lgkmcnt(2)
	v_cndmask_b32_e64 v1, v0, v34, s[4:5]
	s_waitcnt lgkmcnt(1)
	v_cndmask_b32_e64 v39, v40, v9, s[4:5]
	v_cndmask_b32_e64 v0, v34, v0, s[4:5]
	v_cndmask_b32_e64 v40, v9, v40, s[4:5]
	ds_bpermute_b32 v44, v137, v22
	v_mul_f32_e32 v41, v38, v0
	v_fmac_f32_e32 v40, v0, v36
	v_mul_f32_e32 v42, v1, v41
	v_fmac_f32_e32 v39, v1, v40
	s_waitcnt lgkmcnt(1)
	v_cndmask_b32_e64 v0, v8, v33, s[4:5]
	v_cndmask_b32_e64 v1, v33, v8, s[4:5]
	ds_bpermute_b32 v8, v137, v32
	ds_bpermute_b32 v47, v137, v25
	s_waitcnt lgkmcnt(2)
	v_cndmask_b32_e64 v43, v44, v22, s[4:5]
	v_cndmask_b32_e64 v44, v22, v44, s[4:5]
	v_mul_f32_e32 v45, v1, v42
	v_fmac_f32_e32 v44, v1, v39
	v_mul_f32_e32 v46, v0, v45
	v_fmac_f32_e32 v43, v0, v44
	s_waitcnt lgkmcnt(1)
	v_cndmask_b32_e64 v0, v32, v8, s[4:5]
	s_waitcnt lgkmcnt(0)
	v_cndmask_b32_e64 v47, v25, v47, s[4:5]
	v_mul_f32_e32 v88, v0, v46
	v_fmac_f32_e32 v47, v0, v43
	s_and_saveexec_b64 s[6:7], s[4:5]
	v_mul_f32_e32 v0, v32, v88
	v_fma_f32 v1, v32, v47, v25
	ds_write_b64 v136, v[0:1]
	s_or_b64 exec, exec, s[6:7]
	s_cmp_lt_i32 s64, 7
	s_cselect_b64 s[14:15], -1, 0
	s_cmp_gt_i32 s64, 6
	v_mul_i32_i24_e32 v140, 0xffffff08, v93
	s_waitcnt lgkmcnt(0)
	s_barrier
	s_cbranch_scc1 .LBB0_269
	v_add3_u32 v94, v140, v91, s92
	v_mov_b32_e32 v8, 1.0
	v_mov_b32_e32 v1, 0
	s_mov_b32 s6, 7

.LBB0_301:
	v_mov_b32_e32 v92, v177
	s_andn2_b64 vcc, exec, s[0:1]
	v_readfirstlane_b32 s89, v92
	s_waitcnt vmcnt(4)
	v_lshlrev_b32_e32 v8, 4, v92
	s_cbranch_vccnz .LBB0_320
	s_barrier
	s_waitcnt vmcnt(0)
	v_mul_f32_e32 v91, 0xbfb8aa3b, v91
	v_exp_f32_e32 v160, v91
	s_nop 0
	v_add_f32_e32 v35, 1.0, v160
	v_frexp_mant_f32_e32 v154, v35
	v_cvt_f64_f32_e32 v[16:17], v35
	v_add_f32_e32 v153, -1.0, v35
	v_frexp_exp_i32_f64_e32 v16, v[16:17]
	v_cmp_gt_f32_e32 vcc, s84, v154
	v_sub_f32_e32 v34, v153, v35
	v_subbrev_co_u32_e32 v16, vcc, 0, v16, vcc
	v_sub_f32_e32 v153, v160, v153
	v_add_f32_e32 v17, 1.0, v34
	v_sub_u32_e32 v32, 0, v16
	v_add_f32_e32 v17, v153, v17
	v_ldexp_f32 v33, v35, v32
	v_ldexp_f32 v17, v17, v32
	v_add_f32_e32 v32, -1.0, v33
	v_add_f32_e32 v34, 1.0, v33
	v_add_f32_e32 v35, 1.0, v32
	v_add_f32_e32 v91, -1.0, v34
	v_sub_f32_e32 v35, v33, v35
	v_sub_f32_e32 v33, v33, v91
	v_add_f32_e32 v35, v17, v35
	v_add_f32_e32 v17, v17, v33
	v_add_f32_e32 v91, v34, v17
	v_rcp_f32_e32 v154, v91
	v_add_f32_e32 v33, v32, v35
	v_sub_f32_e32 v34, v91, v34
	v_mul_f32_e32 v156, v33, v154
	v_sub_f32_e32 v17, v17, v34
	v_mul_f32_e32 v34, v91, v156
	v_fma_f32 v152, v156, v91, -v34
	v_sub_f32_e32 v32, v33, v32
	v_fmac_f32_e32 v152, v156, v17
	v_sub_f32_e32 v155, v35, v32
	v_add_f32_e32 v32, v34, v152
	v_sub_f32_e32 v35, v33, v32
	v_mov_b32_e32 v153, v32
	v_pk_add_f32 v[32:33], v[32:33], v[34:35] neg_lo:[0,1] neg_hi:[0,1]
	v_cvt_f32_i32_e32 v16, v16
	v_pk_add_f32 v[32:33], v[32:33], v[152:153] neg_lo:[0,1] neg_hi:[0,1]
	v_cmp_neq_f32_e32 vcc, s86, v160
	v_add_f32_e32 v33, v155, v33
	v_add_f32_e32 v32, v32, v33
	v_add_f32_e32 v33, v35, v32
	v_mul_f32_e32 v153, v154, v33
	v_mul_f32_e32 v34, v91, v153
	v_sub_f32_e32 v35, v35, v33
	v_add_f32_e32 v157, v156, v153
	v_fma_f32 v152, v153, v91, -v34
	v_add_f32_e32 v155, v32, v35
	v_sub_f32_e32 v32, v157, v156
	v_fmac_f32_e32 v152, v153, v17
	v_sub_f32_e32 v17, v153, v32
	v_add_f32_e32 v32, v34, v152
	v_sub_f32_e32 v35, v33, v32
	v_mov_b32_e32 v153, v32
	v_pk_add_f32 v[32:33], v[32:33], v[34:35] neg_lo:[0,1] neg_hi:[0,1]
	v_pk_add_f32 v[32:33], v[32:33], v[152:153] neg_lo:[0,1] neg_hi:[0,1]
	v_add_f32_e32 v33, v155, v33
	v_add_f32_e32 v32, v32, v33
	v_add_f32_e32 v32, v35, v32
	v_mul_f32_e32 v32, v154, v32
	v_add_f32_e32 v17, v17, v32
	v_add_f32_e32 v32, v157, v17
	v_mul_f32_e32 v34, v32, v32
	v_sub_f32_e32 v35, v32, v157
	v_fmamk_f32 v91, v34, 0x3e9b6dac, v133
	v_sub_f32_e32 v35, v17, v35
	v_mul_f32_e32 v17, v32, v34
	v_fmaak_f32 v91, v34, v91, 0x3f2aaada
	v_ldexp_f32 v153, v35, 1
	v_pk_mul_f32 v[34:35], v[16:17], v[90:91]
	v_ldexp_f32 v33, v32, 1
	v_fma_f32 v32, v16, s85, -v34
	v_fmac_f32_e32 v32, 0xb102e308, v16
	v_pk_add_f32 v[16:17], v[34:35], v[32:33]
	v_mov_b32_e32 v152, v34
	v_sub_f32_e32 v91, v17, v33
	v_pk_add_f32 v[154:155], v[16:17], v[34:35] neg_lo:[0,1] neg_hi:[0,1]
	v_sub_f32_e32 v34, v35, v91
	v_add_f32_e32 v153, v153, v34
	v_pk_add_f32 v[34:35], v[16:17], v[152:153]
	v_mov_b32_e32 v33, v16
	v_mov_b32_e32 v155, v35
	v_pk_add_f32 v[158:159], v[32:33], v[154:155] neg_lo:[0,1] neg_hi:[0,1]
	v_pk_add_f32 v[32:33], v[32:33], v[154:155]
	v_mov_b32_e32 v157, v16
	v_pk_add_f32 v[154:155], v[32:33], v[16:17] op_sel:[1,0] op_sel_hi:[0,1] neg_lo:[0,1] neg_hi:[0,1]
	v_mov_b32_e32 v156, v153
	v_mov_b32_e32 v152, v35
	v_mov_b32_e32 v153, v33
	v_pk_mov_b32 v[16:17], v[16:17], v[154:155] op_sel:[1,0]
	v_pk_add_f32 v[34:35], v[34:35], v[154:155] op_sel_hi:[1,0] neg_lo:[0,1] neg_hi:[0,1]
	v_pk_add_f32 v[16:17], v[152:153], v[16:17] neg_lo:[0,1] neg_hi:[0,1]
	v_mov_b32_e32 v34, v158
	v_pk_add_f32 v[16:17], v[156:157], v[16:17] neg_lo:[0,1] neg_hi:[0,1]
	v_mov_b32_e32 v159, v33
	v_pk_add_f32 v[34:35], v[34:35], v[16:17]
	v_pk_add_f32 v[152:153], v[34:35], v[34:35] op_sel:[0,1] op_sel_hi:[1,0]
	v_pk_add_f32 v[32:33], v[32:33], v[152:153] op_sel:[1,0] op_sel_hi:[0,1]
	v_mov_b32_e32 v35, v32
	v_mov_b32_e32 v17, v152
	v_pk_add_f32 v[152:153], v[34:35], v[158:159] neg_lo:[0,1] neg_hi:[0,1]
	v_sub_f32_e32 v33, v34, v152
	v_pk_add_f32 v[16:17], v[16:17], v[152:153] neg_lo:[0,1] neg_hi:[0,1]
	v_sub_f32_e32 v33, v158, v33
	v_add_f32_e32 v16, v16, v33
	v_add_f32_e32 v16, v16, v17
	v_add_f32_e32 v16, v32, v16
	v_cndmask_b32_e32 v16, v135, v16, vcc
	v_cmp_ngt_f32_e32 vcc, -1.0, v160
	v_cndmask_b32_e32 v16, v136, v16, vcc
	v_cmp_neq_f32_e32 vcc, -1.0, v160
	v_cndmask_b32_e32 v16, v137, v16, vcc
	v_cmp_lt_f32_e64 vcc, |v160|, s87
	v_cndmask_b32_e32 v16, v16, v160, vcc
	v_mul_f32_e32 v33, 0xc1000000, v16
	ds_write_b32 v138, v33
	v_and_b32_e32 v238, 0x7f, v177
	v_lshrrev_b32_e32 v239, 7, v177
	v_or_b32_e32 v238, s70, v238
	v_lshl_or_b32 v238, v239, 10, v238
	v_lshlrev_b32_e32 v238, 2, v238
	global_load_dword v240, v238, s[26:27]
	v_or_b32_e32 v239, s70, v177
	v_lshlrev_b32_e32 v239, 2, v239
	v_cmp_gt_u32_e32 vcc, 0x80, v177
	s_and_saveexec_b64 s[100:101], vcc
	global_load_dword v241, v239, s[28:29]
	s_mov_b64 exec, s[100:101]
	v_add_u32_e32 v93, 0x200, v92
	v_add_u32_e32 v10, 0x400, v92
	v_add_u32_e32 v12, 0x600, v92
	v_add_u32_e32 v18, 0x800, v92
	v_add_u32_e32 v20, 0xa00, v92
	v_add_u32_e32 v28, 0xc00, v92
	v_add_u32_e32 v30, 0xe00, v92
	v_ashrrev_i32_e32 v9, 4, v92
	s_waitcnt vmcnt(3)
	v_ashrrev_i32_e32 v34, 4, v93
	v_ashrrev_i32_e32 v35, 4, v10
	v_ashrrev_i32_e32 v36, 4, v12
	v_ashrrev_i32_e32 v37, 4, v18
	v_ashrrev_i32_e32 v38, 4, v20
	v_ashrrev_i32_e32 v39, 4, v28
	v_ashrrev_i32_e32 v40, 4, v30
	v_and_b32_e32 v88, 0xf0, v8
	v_lshlrev_b32_e32 v0, 7, v9
	v_lshlrev_b32_e32 v2, 7, v34
	v_lshlrev_b32_e32 v10, 7, v35
	v_lshlrev_b32_e32 v12, 7, v36
	v_lshlrev_b32_e32 v18, 7, v37
	v_lshlrev_b32_e32 v20, 7, v38
	v_lshlrev_b32_e32 v28, 7, v39
	v_lshlrev_b32_e32 v30, 7, v40
	v_lshl_add_u64 v[26:27], s[20:21], 0, v[88:89]
	v_ashrrev_i32_e32 v1, 31, v0
	v_ashrrev_i32_e32 v3, 31, v2
	v_ashrrev_i32_e32 v11, 31, v10
	v_ashrrev_i32_e32 v13, 31, v12
	v_ashrrev_i32_e32 v19, 31, v18
	v_ashrrev_i32_e32 v21, 31, v20
	v_ashrrev_i32_e32 v29, 31, v28
	v_ashrrev_i32_e32 v31, 31, v30
	v_lshl_add_u64 v[0:1], v[0:1], 1, v[26:27]
	v_lshl_add_u64 v[4:5], v[2:3], 1, v[26:27]
	v_lshl_add_u64 v[10:11], v[10:11], 1, v[26:27]
	v_lshl_add_u64 v[14:15], v[12:13], 1, v[26:27]
	v_lshl_add_u64 v[18:19], v[18:19], 1, v[26:27]
	v_lshl_add_u64 v[22:23], v[20:21], 1, v[26:27]
	v_lshl_add_u64 v[28:29], v[28:29], 1, v[26:27]
	v_lshl_add_u64 v[30:31], v[30:31], 1, v[26:27]
	global_load_dwordx4 v[0:3], v[0:1], off
	s_nop 0
	global_load_dwordx4 v[4:7], v[4:5], off
	s_nop 0
	global_load_dwordx4 v[10:13], v[10:11], off
	s_nop 0
	global_load_dwordx4 v[14:17], v[14:15], off
	s_nop 0
	global_load_dwordx4 v[18:21], v[18:19], off
	s_nop 0
	global_load_dwordx4 v[22:25], v[22:23], off
	s_nop 0
	global_load_dwordx4 v[26:29], v[28:29], off
	s_nop 0
	global_load_dwordx4 v[30:33], v[30:31], off
	v_and_b32_e32 v41, 0x70, v92
	v_xad_u32 v41, v88, v41, 16
	v_lshl_add_u32 v9, v9, 8, v41
	v_cmp_gt_i32_e32 vcc, s75, v92
	v_lshl_add_u32 v34, v34, 8, v41
	v_lshl_add_u32 v35, v35, 8, v41
	v_lshl_add_u32 v36, v36, 8, v41
	v_lshl_add_u32 v37, v37, 8, v41
	v_lshl_add_u32 v38, v38, 8, v41
	v_lshl_add_u32 v39, v39, 8, v41
	v_lshl_add_u32 v40, v40, 8, v41
	s_waitcnt vmcnt(7)
	ds_write_b128 v9, v[0:3] offset:16384
	s_waitcnt vmcnt(6)
	ds_write_b128 v34, v[4:7] offset:16384
	s_waitcnt vmcnt(5)
	ds_write_b128 v35, v[10:13] offset:16384
	s_waitcnt vmcnt(4)
	ds_write_b128 v36, v[14:17] offset:16384
	s_waitcnt vmcnt(3)
	ds_write_b128 v37, v[18:21] offset:16384
	s_waitcnt vmcnt(2)
	ds_write_b128 v38, v[22:25] offset:16384
	s_waitcnt vmcnt(1)
	ds_write_b128 v39, v[26:29] offset:16384
	s_waitcnt vmcnt(0)
	ds_write_b128 v40, v[30:33] offset:16384
	v_lshl_add_u32 v238, v177, 2, s78
	ds_write_b32 v238, v240
	v_cmp_gt_u32_e32 vcc, 0x80, v177
	s_and_saveexec_b64 s[100:101], vcc
	ds_write_b32 v238, v241 offset:2048
	s_mov_b64 exec, s[100:101]

.LBB0_320:
	s_and_b32 s63, s57, 63
	s_ashr_i32 s62, s89, 6
	s_lshl_b32 s0, s63, 8
	s_lshl_b32 s1, s62, 5
	v_and_b32_e32 v94, 31, v92
	s_add_i32 s8, s1, s0
	v_or_b32_e32 v9, s8, v94
	v_add_u32_e32 v0, -2, v9
	v_cmp_gt_u32_e32 vcc, s80, v0
	v_bfe_u32 v93, v92, 5, 1
	s_lshl_b32 s14, s70, 1
	v_cndmask_b32_e32 v2, v9, v0, vcc
	v_mov_b64_e32 v[0:1], s[52:53]
	v_mad_i64_i32 v[2:3], s[0:1], v2, s81, v[0:1]
	v_lshl_add_u64 v[2:3], v[2:3], 0, s[14:15]
	v_lshlrev_b32_e32 v88, 4, v93
	v_lshl_add_u64 v[4:5], v[2:3], 0, v[88:89]
	v_add_co_u32_e64 v2, s[0:1], s82, v4
	s_waitcnt lgkmcnt(0)
	s_nop 0
	v_addc_co_u32_e64 v3, s[0:1], 0, v5, s[0:1]
	global_load_dwordx4 v[10:13], v[2:3], off offset:1024
	global_load_dwordx4 v[178:181], v[2:3], off offset:1056
	global_load_dwordx4 v[194:197], v[2:3], off offset:1088
	global_load_dwordx4 v[210:213], v[2:3], off offset:1120
	global_load_dwordx4 v[226:229], v[2:3], off offset:1152
	global_load_dwordx4 v[242:245], v[2:3], off offset:1184
	v_add_u32_e32 v2, -1, v9
	v_cmp_gt_u32_e64 s[0:1], s80, v2
	v_add_u32_e32 v18, 1, v9
	s_cmpk_lt_u32 s8, 0x4000
	v_cndmask_b32_e64 v2, v9, v2, s[0:1]
	v_mad_i64_i32 v[2:3], s[4:5], v2, s81, v[0:1]
	v_lshl_add_u64 v[2:3], v[2:3], 0, s[14:15]
	v_lshl_add_u64 v[2:3], v[2:3], 0, v[88:89]
	v_add_co_u32_e64 v6, s[4:5], s82, v2
	v_lshlrev_b32_e32 v138, 8, v94
	s_nop 0
	v_addc_co_u32_e64 v7, s[4:5], 0, v3, s[4:5]
	global_load_dwordx4 v[14:17], v[6:7], off offset:1024
	global_load_dwordx4 v[182:185], v[6:7], off offset:1056
	global_load_dwordx4 v[198:201], v[6:7], off offset:1088
	global_load_dwordx4 v[214:217], v[6:7], off offset:1120
	global_load_dwordx4 v[230:233], v[6:7], off offset:1152
	global_load_dwordx4 v[246:249], v[6:7], off offset:1184
	v_mad_i64_i32 v[6:7], s[4:5], v9, s81, v[0:1]
	v_cmp_gt_u32_e64 s[4:5], s80, v18
	v_lshl_add_u64 v[6:7], v[6:7], 0, s[14:15]
	v_lshl_add_u64 v[52:53], v[6:7], 0, v[88:89]
	v_cndmask_b32_e64 v9, v9, v18, s[4:5]
	v_mad_i64_i32 v[0:1], s[6:7], v9, s81, v[0:1]
	v_add_co_u32_e64 v6, s[6:7], s82, v52
	v_lshl_add_u64 v[0:1], v[0:1], 0, s[14:15]
	s_nop 0
	v_addc_co_u32_e64 v7, s[6:7], 0, v53, s[6:7]
	global_load_dwordx4 v[18:21], v[6:7], off offset:1024
	global_load_dwordx4 v[186:189], v[6:7], off offset:1056
	global_load_dwordx4 v[202:205], v[6:7], off offset:1088
	global_load_dwordx4 v[218:221], v[6:7], off offset:1120
	global_load_dwordx4 v[234:237], v[6:7], off offset:1152
	global_load_dwordx4 v[252:255], v[6:7], off offset:1184
	v_lshl_add_u64 v[6:7], v[0:1], 0, v[88:89]
	v_add_co_u32_e64 v0, s[6:7], s82, v6
	v_lshl_add_u32 v9, v93, 5, 16
	s_nop 0
	v_addc_co_u32_e64 v1, s[6:7], 0, v7, s[6:7]
	global_load_dwordx4 v[22:25], v[0:1], off offset:1024
	global_load_dwordx4 v[190:193], v[0:1], off offset:1056
	global_load_dwordx4 v[206:209], v[0:1], off offset:1088
	global_load_dwordx4 v[222:225], v[0:1], off offset:1120
	global_load_dwordx4 v[238:241], v[0:1], off offset:1152
	global_load_dwordx4 v[168:171], v[0:1], off offset:1184
	s_waitcnt vmcnt(26)
	s_waitcnt lgkmcnt(4)
	v_lshl_add_u64 v[0:1], v[4:5], 0, s[30:31]
	s_cselect_b64 s[6:7], -1, 0
	v_lshl_add_u64 v[6:7], v[6:7], 0, s[30:31]
	v_and_b32_e32 v8, 0x70, v8
	v_add_u32_e32 v95, 16, v138
	v_or_b32_e32 v91, s70, v94
	s_waitcnt vmcnt(23)
	s_waitcnt vmcnt(17)
	s_waitcnt lgkmcnt(3)
	s_waitcnt lgkmcnt(1)
	s_waitcnt lgkmcnt(0)
	s_waitcnt vmcnt(11)
	s_waitcnt vmcnt(5)
	ds_read_b128 v[26:29], v9 offset:10240
	ds_read_b128 v[30:33], v9 offset:10256
	ds_read_b128 v[34:37], v9 offset:8192
	ds_read_b128 v[38:41], v9 offset:8208
	ds_read_b128 v[42:45], v9 offset:8704
	ds_read_b128 v[80:83], v9 offset:8720
	s_mov_b64 exec, vcc
	v_lshlrev_b32_e32 v4, 16, v10
	v_and_b32_e32 v5, 0xffff0000, v10
	v_lshlrev_b32_e32 v46, 16, v11
	v_and_b32_e32 v47, 0xffff0000, v11
	s_waitcnt lgkmcnt(2)
	v_pk_fma_f32 v[26:27], v[34:35], v[4:5], v[26:27]
	v_pk_fma_f32 v[28:29], v[36:37], v[46:47], v[28:29]
	v_lshlrev_b32_e32 v84, 16, v12
	v_and_b32_e32 v85, 0xffff0000, v12
	v_lshlrev_b32_e32 v86, 16, v13
	v_and_b32_e32 v87, 0xffff0000, v13
	v_pk_fma_f32 v[30:31], v[38:39], v[84:85], v[30:31]
	v_pk_fma_f32 v[32:33], v[40:41], v[86:87], v[32:33]
	s_mov_b64 exec, -1
	ds_read_b128 v[34:37], v9 offset:9216
	ds_read_b128 v[38:41], v9 offset:9232
	s_mov_b64 exec, s[0:1]
	v_lshlrev_b32_e32 v4, 16, v14
	v_and_b32_e32 v5, 0xffff0000, v14
	v_lshlrev_b32_e32 v46, 16, v15
	v_and_b32_e32 v47, 0xffff0000, v15
	s_waitcnt lgkmcnt(2)
	v_pk_fma_f32 v[26:27], v[42:43], v[4:5], v[26:27]
	v_pk_fma_f32 v[28:29], v[44:45], v[46:47], v[28:29]
	v_lshlrev_b32_e32 v84, 16, v16
	v_and_b32_e32 v85, 0xffff0000, v16
	v_lshlrev_b32_e32 v86, 16, v17
	v_and_b32_e32 v87, 0xffff0000, v17
	v_pk_fma_f32 v[30:31], v[80:81], v[84:85], v[30:31]
	v_pk_fma_f32 v[32:33], v[82:83], v[86:87], v[32:33]
	s_mov_b64 exec, -1
	ds_read_b128 v[42:45], v9 offset:9728
	ds_read_b128 v[80:83], v9 offset:9744
	v_lshlrev_b32_e32 v4, 16, v18
	v_and_b32_e32 v5, 0xffff0000, v18
	v_lshlrev_b32_e32 v46, 16, v19
	v_and_b32_e32 v47, 0xffff0000, v19
	s_waitcnt lgkmcnt(2)
	v_pk_fma_f32 v[26:27], v[34:35], v[4:5], v[26:27]
	v_pk_fma_f32 v[28:29], v[36:37], v[46:47], v[28:29]
	v_lshlrev_b32_e32 v84, 16, v20
	v_and_b32_e32 v85, 0xffff0000, v20
	v_lshlrev_b32_e32 v86, 16, v21
	v_and_b32_e32 v87, 0xffff0000, v21
	v_pk_fma_f32 v[30:31], v[38:39], v[84:85], v[30:31]
	v_pk_fma_f32 v[32:33], v[40:41], v[86:87], v[32:33]
	s_mov_b64 exec, s[4:5]
	v_lshlrev_b32_e32 v4, 16, v22
	v_and_b32_e32 v5, 0xffff0000, v22
	v_lshlrev_b32_e32 v46, 16, v23
	v_and_b32_e32 v47, 0xffff0000, v23
	s_waitcnt lgkmcnt(0)
	v_pk_fma_f32 v[26:27], v[42:43], v[4:5], v[26:27]
	v_pk_fma_f32 v[28:29], v[44:45], v[46:47], v[28:29]
	v_lshlrev_b32_e32 v84, 16, v24
	v_and_b32_e32 v85, 0xffff0000, v24
	v_lshlrev_b32_e32 v86, 16, v25
	v_and_b32_e32 v87, 0xffff0000, v25
	v_pk_fma_f32 v[30:31], v[80:81], v[84:85], v[30:31]
	v_pk_fma_f32 v[32:33], v[82:83], v[86:87], v[32:33]
	s_mov_b64 exec, -1
	v_cvt_pk_bf16_f32 v48, v26, v27
	v_cvt_pk_bf16_f32 v49, v28, v29
	v_cvt_pk_bf16_f32 v50, v30, v31
	v_cvt_pk_bf16_f32 v51, v32, v33
	s_waitcnt lgkmcnt(3)
	s_waitcnt lgkmcnt(1)
	s_waitcnt lgkmcnt(0)
	s_nop 0
	v_lshl_add_u64 v[4:5], v[2:3], 0, s[30:31]
	v_lshl_add_u64 v[2:3], v[52:53], 0, s[30:31]
	s_waitcnt vmcnt(4)
	s_waitcnt vmcnt(4)
	s_waitcnt lgkmcnt(3)
	s_waitcnt lgkmcnt(1)
	s_waitcnt lgkmcnt(0)
	s_waitcnt vmcnt(4)
	ds_read_b128 v[26:29], v9 offset:10304
	ds_read_b128 v[30:33], v9 offset:10320
	ds_read_b128 v[34:37], v9 offset:8256
	ds_read_b128 v[38:41], v9 offset:8272
	ds_read_b128 v[42:45], v9 offset:8768
	ds_read_b128 v[80:83], v9 offset:8784
	s_mov_b64 exec, vcc
	v_lshlrev_b32_e32 v46, 16, v178
	v_and_b32_e32 v47, 0xffff0000, v178
	v_lshlrev_b32_e32 v84, 16, v179
	v_and_b32_e32 v85, 0xffff0000, v179
	s_waitcnt lgkmcnt(2)
	v_pk_fma_f32 v[26:27], v[34:35], v[46:47], v[26:27]
	v_pk_fma_f32 v[28:29], v[36:37], v[84:85], v[28:29]
	v_lshlrev_b32_e32 v86, 16, v180
	v_and_b32_e32 v87, 0xffff0000, v180
	v_lshlrev_b32_e32 v96, 16, v181
	v_and_b32_e32 v97, 0xffff0000, v181
	v_pk_fma_f32 v[30:31], v[38:39], v[86:87], v[30:31]
	v_pk_fma_f32 v[32:33], v[40:41], v[96:97], v[32:33]
	s_mov_b64 exec, -1
	ds_read_b128 v[34:37], v9 offset:9280
	ds_read_b128 v[38:41], v9 offset:9296
	s_mov_b64 exec, s[0:1]
	v_lshlrev_b32_e32 v46, 16, v182
	v_and_b32_e32 v47, 0xffff0000, v182
	v_lshlrev_b32_e32 v84, 16, v183
	v_and_b32_e32 v85, 0xffff0000, v183
	s_waitcnt lgkmcnt(2)
	v_pk_fma_f32 v[26:27], v[42:43], v[46:47], v[26:27]
	v_pk_fma_f32 v[28:29], v[44:45], v[84:85], v[28:29]
	v_lshlrev_b32_e32 v86, 16, v184
	v_and_b32_e32 v87, 0xffff0000, v184
	v_lshlrev_b32_e32 v96, 16, v185
	v_and_b32_e32 v97, 0xffff0000, v185
	v_pk_fma_f32 v[30:31], v[80:81], v[86:87], v[30:31]
	v_pk_fma_f32 v[32:33], v[82:83], v[96:97], v[32:33]
	s_mov_b64 exec, -1
	ds_read_b128 v[42:45], v9 offset:9792
	ds_read_b128 v[80:83], v9 offset:9808
	v_lshlrev_b32_e32 v46, 16, v186
	v_and_b32_e32 v47, 0xffff0000, v186
	v_lshlrev_b32_e32 v84, 16, v187
	v_and_b32_e32 v85, 0xffff0000, v187
	s_waitcnt lgkmcnt(2)
	v_pk_fma_f32 v[26:27], v[34:35], v[46:47], v[26:27]
	v_pk_fma_f32 v[28:29], v[36:37], v[84:85], v[28:29]
	v_lshlrev_b32_e32 v86, 16, v188
	v_and_b32_e32 v87, 0xffff0000, v188
	v_lshlrev_b32_e32 v96, 16, v189
	v_and_b32_e32 v97, 0xffff0000, v189
	v_pk_fma_f32 v[30:31], v[38:39], v[86:87], v[30:31]
	v_pk_fma_f32 v[32:33], v[40:41], v[96:97], v[32:33]
	s_mov_b64 exec, s[4:5]
	v_lshlrev_b32_e32 v46, 16, v190
	v_and_b32_e32 v47, 0xffff0000, v190
	v_lshlrev_b32_e32 v84, 16, v191
	v_and_b32_e32 v85, 0xffff0000, v191
	s_waitcnt lgkmcnt(0)
	v_pk_fma_f32 v[26:27], v[42:43], v[46:47], v[26:27]
	v_pk_fma_f32 v[28:29], v[44:45], v[84:85], v[28:29]
	v_lshlrev_b32_e32 v86, 16, v192
	v_and_b32_e32 v87, 0xffff0000, v192
	v_lshlrev_b32_e32 v96, 16, v193
	v_and_b32_e32 v97, 0xffff0000, v193
	v_pk_fma_f32 v[30:31], v[80:81], v[86:87], v[30:31]
	v_pk_fma_f32 v[32:33], v[82:83], v[96:97], v[32:33]
	s_mov_b64 exec, -1
	v_cvt_pk_bf16_f32 v52, v26, v27
	v_cvt_pk_bf16_f32 v53, v28, v29
	v_cvt_pk_bf16_f32 v54, v30, v31
	v_cvt_pk_bf16_f32 v55, v32, v33
	s_waitcnt lgkmcnt(3)
	s_waitcnt lgkmcnt(1)
	s_waitcnt lgkmcnt(0)
	s_nop 0
	global_load_dwordx4 v[178:181], v[0:1], off offset:192
	global_load_dwordx4 v[182:185], v[4:5], off offset:192
	global_load_dwordx4 v[186:189], v[2:3], off offset:192
	global_load_dwordx4 v[190:193], v[6:7], off offset:192
	s_waitcnt vmcnt(7)
	s_waitcnt vmcnt(7)
	s_waitcnt lgkmcnt(3)
	s_waitcnt lgkmcnt(1)
	s_waitcnt lgkmcnt(0)
	s_waitcnt vmcnt(7)
	s_waitcnt vmcnt(7)
	ds_read_b128 v[26:29], v9 offset:10368
	ds_read_b128 v[30:33], v9 offset:10384
	ds_read_b128 v[34:37], v9 offset:8320
	ds_read_b128 v[38:41], v9 offset:8336
	ds_read_b128 v[42:45], v9 offset:8832
	ds_read_b128 v[80:83], v9 offset:8848
	s_mov_b64 exec, vcc
	v_lshlrev_b32_e32 v46, 16, v194
	v_and_b32_e32 v47, 0xffff0000, v194
	v_lshlrev_b32_e32 v84, 16, v195
	v_and_b32_e32 v85, 0xffff0000, v195
	s_waitcnt lgkmcnt(2)
	v_pk_fma_f32 v[26:27], v[34:35], v[46:47], v[26:27]
	v_pk_fma_f32 v[28:29], v[36:37], v[84:85], v[28:29]
	v_lshlrev_b32_e32 v86, 16, v196
	v_and_b32_e32 v87, 0xffff0000, v196
	v_lshlrev_b32_e32 v96, 16, v197
	v_and_b32_e32 v97, 0xffff0000, v197
	v_pk_fma_f32 v[30:31], v[38:39], v[86:87], v[30:31]
	v_pk_fma_f32 v[32:33], v[40:41], v[96:97], v[32:33]
	s_mov_b64 exec, -1
	ds_read_b128 v[34:37], v9 offset:9344
	ds_read_b128 v[38:41], v9 offset:9360
	s_mov_b64 exec, s[0:1]
	v_lshlrev_b32_e32 v46, 16, v198
	v_and_b32_e32 v47, 0xffff0000, v198
	v_lshlrev_b32_e32 v84, 16, v199
	v_and_b32_e32 v85, 0xffff0000, v199
	s_waitcnt lgkmcnt(2)
	v_pk_fma_f32 v[26:27], v[42:43], v[46:47], v[26:27]
	v_pk_fma_f32 v[28:29], v[44:45], v[84:85], v[28:29]
	v_lshlrev_b32_e32 v86, 16, v200
	v_and_b32_e32 v87, 0xffff0000, v200
	v_lshlrev_b32_e32 v96, 16, v201
	v_and_b32_e32 v97, 0xffff0000, v201
	v_pk_fma_f32 v[30:31], v[80:81], v[86:87], v[30:31]
	v_pk_fma_f32 v[32:33], v[82:83], v[96:97], v[32:33]
	s_mov_b64 exec, -1
	ds_read_b128 v[42:45], v9 offset:9856
	ds_read_b128 v[80:83], v9 offset:9872
	v_lshlrev_b32_e32 v46, 16, v202
	v_and_b32_e32 v47, 0xffff0000, v202
	v_lshlrev_b32_e32 v84, 16, v203
	v_and_b32_e32 v85, 0xffff0000, v203
	s_waitcnt lgkmcnt(2)
	v_pk_fma_f32 v[26:27], v[34:35], v[46:47], v[26:27]
	v_pk_fma_f32 v[28:29], v[36:37], v[84:85], v[28:29]
	v_lshlrev_b32_e32 v86, 16, v204
	v_and_b32_e32 v87, 0xffff0000, v204
	v_lshlrev_b32_e32 v96, 16, v205
	v_and_b32_e32 v97, 0xffff0000, v205
	v_pk_fma_f32 v[30:31], v[38:39], v[86:87], v[30:31]
	v_pk_fma_f32 v[32:33], v[40:41], v[96:97], v[32:33]
	s_mov_b64 exec, s[4:5]
	v_lshlrev_b32_e32 v46, 16, v206
	v_and_b32_e32 v47, 0xffff0000, v206
	v_lshlrev_b32_e32 v84, 16, v207
	v_and_b32_e32 v85, 0xffff0000, v207
	s_waitcnt lgkmcnt(0)
	v_pk_fma_f32 v[26:27], v[42:43], v[46:47], v[26:27]
	v_pk_fma_f32 v[28:29], v[44:45], v[84:85], v[28:29]
	v_lshlrev_b32_e32 v86, 16, v208
	v_and_b32_e32 v87, 0xffff0000, v208
	v_lshlrev_b32_e32 v96, 16, v209
	v_and_b32_e32 v97, 0xffff0000, v209
	v_pk_fma_f32 v[30:31], v[80:81], v[86:87], v[30:31]
	v_pk_fma_f32 v[32:33], v[82:83], v[96:97], v[32:33]
	s_mov_b64 exec, -1
	v_cvt_pk_bf16_f32 v56, v26, v27
	v_cvt_pk_bf16_f32 v57, v28, v29
	v_cvt_pk_bf16_f32 v58, v30, v31
	v_cvt_pk_bf16_f32 v59, v32, v33
	s_waitcnt lgkmcnt(3)
	s_waitcnt lgkmcnt(1)
	s_waitcnt lgkmcnt(0)
	s_nop 0
	global_load_dwordx4 v[194:197], v[0:1], off offset:224
	global_load_dwordx4 v[198:201], v[4:5], off offset:224
	global_load_dwordx4 v[202:205], v[2:3], off offset:224
	global_load_dwordx4 v[206:209], v[6:7], off offset:224
	s_waitcnt vmcnt(10)
	s_waitcnt vmcnt(10)
	s_waitcnt lgkmcnt(3)
	s_waitcnt lgkmcnt(1)
	s_waitcnt lgkmcnt(0)
	s_waitcnt vmcnt(10)
	s_waitcnt vmcnt(10)
	ds_read_b128 v[0:3], v9 offset:10432
	ds_read_b128 v[4:7], v9 offset:10448
	ds_read_b128 v[26:29], v9 offset:8384
	ds_read_b128 v[30:33], v9 offset:8400
	ds_read_b128 v[34:37], v9 offset:8896
	ds_read_b128 v[38:41], v9 offset:8912
	s_mov_b64 exec, vcc
	v_lshlrev_b32_e32 v42, 16, v210
	v_and_b32_e32 v43, 0xffff0000, v210
	v_lshlrev_b32_e32 v44, 16, v211
	v_and_b32_e32 v45, 0xffff0000, v211
	s_waitcnt lgkmcnt(2)
	v_pk_fma_f32 v[0:1], v[26:27], v[42:43], v[0:1]
	v_pk_fma_f32 v[2:3], v[28:29], v[44:45], v[2:3]
	v_lshlrev_b32_e32 v46, 16, v212
	v_and_b32_e32 v47, 0xffff0000, v212
	v_lshlrev_b32_e32 v80, 16, v213
	v_and_b32_e32 v81, 0xffff0000, v213
	v_pk_fma_f32 v[4:5], v[30:31], v[46:47], v[4:5]
	v_pk_fma_f32 v[6:7], v[32:33], v[80:81], v[6:7]
	s_mov_b64 exec, -1
	ds_read_b128 v[26:29], v9 offset:9408
	ds_read_b128 v[30:33], v9 offset:9424
	s_mov_b64 exec, s[0:1]
	v_lshlrev_b32_e32 v42, 16, v214
	v_and_b32_e32 v43, 0xffff0000, v214
	v_lshlrev_b32_e32 v44, 16, v215
	v_and_b32_e32 v45, 0xffff0000, v215
	s_waitcnt lgkmcnt(2)
	v_pk_fma_f32 v[0:1], v[34:35], v[42:43], v[0:1]
	v_pk_fma_f32 v[2:3], v[36:37], v[44:45], v[2:3]
	v_lshlrev_b32_e32 v46, 16, v216
	v_and_b32_e32 v47, 0xffff0000, v216
	v_lshlrev_b32_e32 v80, 16, v217
	v_and_b32_e32 v81, 0xffff0000, v217
	v_pk_fma_f32 v[4:5], v[38:39], v[46:47], v[4:5]
	v_pk_fma_f32 v[6:7], v[40:41], v[80:81], v[6:7]
	s_mov_b64 exec, -1
	ds_read_b128 v[34:37], v9 offset:9920
	ds_read_b128 v[38:41], v9 offset:9936
	v_lshlrev_b32_e32 v42, 16, v218
	v_and_b32_e32 v43, 0xffff0000, v218
	v_lshlrev_b32_e32 v44, 16, v219
	v_and_b32_e32 v45, 0xffff0000, v219
	s_waitcnt lgkmcnt(2)
	v_pk_fma_f32 v[0:1], v[26:27], v[42:43], v[0:1]
	v_pk_fma_f32 v[2:3], v[28:29], v[44:45], v[2:3]
	v_lshlrev_b32_e32 v46, 16, v220
	v_and_b32_e32 v47, 0xffff0000, v220
	v_lshlrev_b32_e32 v80, 16, v221
	v_and_b32_e32 v81, 0xffff0000, v221
	v_pk_fma_f32 v[4:5], v[30:31], v[46:47], v[4:5]
	v_pk_fma_f32 v[6:7], v[32:33], v[80:81], v[6:7]
	s_mov_b64 exec, s[4:5]
	v_lshlrev_b32_e32 v42, 16, v222
	v_and_b32_e32 v43, 0xffff0000, v222
	v_lshlrev_b32_e32 v44, 16, v223
	v_and_b32_e32 v45, 0xffff0000, v223
	s_waitcnt lgkmcnt(0)
	v_pk_fma_f32 v[0:1], v[34:35], v[42:43], v[0:1]
	v_pk_fma_f32 v[2:3], v[36:37], v[44:45], v[2:3]
	v_lshlrev_b32_e32 v46, 16, v224
	v_and_b32_e32 v47, 0xffff0000, v224
	v_lshlrev_b32_e32 v80, 16, v225
	v_and_b32_e32 v81, 0xffff0000, v225
	v_pk_fma_f32 v[4:5], v[38:39], v[46:47], v[4:5]
	v_pk_fma_f32 v[6:7], v[40:41], v[80:81], v[6:7]
	s_mov_b64 exec, -1
	v_cvt_pk_bf16_f32 v60, v0, v1
	v_cvt_pk_bf16_f32 v61, v2, v3
	v_cvt_pk_bf16_f32 v62, v4, v5
	v_cvt_pk_bf16_f32 v63, v6, v7
	s_waitcnt lgkmcnt(3)
	s_waitcnt lgkmcnt(1)
	s_waitcnt lgkmcnt(0)
	s_nop 0
	s_waitcnt vmcnt(9)
	s_waitcnt vmcnt(9)
	s_waitcnt lgkmcnt(3)
	s_waitcnt lgkmcnt(1)
	s_waitcnt lgkmcnt(0)
	s_waitcnt vmcnt(9)
	s_waitcnt vmcnt(9)
	ds_read_b128 v[0:3], v9 offset:10496
	ds_read_b128 v[4:7], v9 offset:10512
	ds_read_b128 v[26:29], v9 offset:8448
	ds_read_b128 v[30:33], v9 offset:8464
	ds_read_b128 v[34:37], v9 offset:8960
	ds_read_b128 v[38:41], v9 offset:8976
	s_mov_b64 exec, vcc
	v_lshlrev_b32_e32 v42, 16, v226
	v_and_b32_e32 v43, 0xffff0000, v226
	v_lshlrev_b32_e32 v44, 16, v227
	v_and_b32_e32 v45, 0xffff0000, v227
	s_waitcnt lgkmcnt(2)
	v_pk_fma_f32 v[0:1], v[26:27], v[42:43], v[0:1]
	v_pk_fma_f32 v[2:3], v[28:29], v[44:45], v[2:3]
	v_lshlrev_b32_e32 v46, 16, v228
	v_and_b32_e32 v47, 0xffff0000, v228
	v_lshlrev_b32_e32 v80, 16, v229
	v_and_b32_e32 v81, 0xffff0000, v229
	v_pk_fma_f32 v[4:5], v[30:31], v[46:47], v[4:5]
	v_pk_fma_f32 v[6:7], v[32:33], v[80:81], v[6:7]
	s_mov_b64 exec, -1
	ds_read_b128 v[26:29], v9 offset:9472
	ds_read_b128 v[30:33], v9 offset:9488
	s_mov_b64 exec, s[0:1]
	v_lshlrev_b32_e32 v42, 16, v230
	v_and_b32_e32 v43, 0xffff0000, v230
	v_lshlrev_b32_e32 v44, 16, v231
	v_and_b32_e32 v45, 0xffff0000, v231
	s_waitcnt lgkmcnt(2)
	v_pk_fma_f32 v[0:1], v[34:35], v[42:43], v[0:1]
	v_pk_fma_f32 v[2:3], v[36:37], v[44:45], v[2:3]
	v_lshlrev_b32_e32 v46, 16, v232
	v_and_b32_e32 v47, 0xffff0000, v232
	v_lshlrev_b32_e32 v80, 16, v233
	v_and_b32_e32 v81, 0xffff0000, v233
	v_pk_fma_f32 v[4:5], v[38:39], v[46:47], v[4:5]
	v_pk_fma_f32 v[6:7], v[40:41], v[80:81], v[6:7]
	s_mov_b64 exec, -1
	ds_read_b128 v[34:37], v9 offset:9984
	ds_read_b128 v[38:41], v9 offset:10000
	v_lshlrev_b32_e32 v42, 16, v234
	v_and_b32_e32 v43, 0xffff0000, v234
	v_lshlrev_b32_e32 v44, 16, v235
	v_and_b32_e32 v45, 0xffff0000, v235
	s_waitcnt lgkmcnt(2)
	v_pk_fma_f32 v[0:1], v[26:27], v[42:43], v[0:1]
	v_pk_fma_f32 v[2:3], v[28:29], v[44:45], v[2:3]
	v_lshlrev_b32_e32 v46, 16, v236
	v_and_b32_e32 v47, 0xffff0000, v236
	v_lshlrev_b32_e32 v80, 16, v237
	v_and_b32_e32 v81, 0xffff0000, v237
	v_pk_fma_f32 v[4:5], v[30:31], v[46:47], v[4:5]
	v_pk_fma_f32 v[6:7], v[32:33], v[80:81], v[6:7]
	s_mov_b64 exec, s[4:5]
	v_lshlrev_b32_e32 v42, 16, v238
	v_and_b32_e32 v43, 0xffff0000, v238
	v_lshlrev_b32_e32 v44, 16, v239
	v_and_b32_e32 v45, 0xffff0000, v239
	s_waitcnt lgkmcnt(0)
	v_pk_fma_f32 v[0:1], v[34:35], v[42:43], v[0:1]
	v_pk_fma_f32 v[2:3], v[36:37], v[44:45], v[2:3]
	v_lshlrev_b32_e32 v46, 16, v240
	v_and_b32_e32 v47, 0xffff0000, v240
	v_lshlrev_b32_e32 v80, 16, v241
	v_and_b32_e32 v81, 0xffff0000, v241
	v_pk_fma_f32 v[4:5], v[38:39], v[46:47], v[4:5]
	v_pk_fma_f32 v[6:7], v[40:41], v[80:81], v[6:7]
	s_mov_b64 exec, -1
	v_cvt_pk_bf16_f32 v64, v0, v1
	v_cvt_pk_bf16_f32 v65, v2, v3
	v_cvt_pk_bf16_f32 v66, v4, v5
	v_cvt_pk_bf16_f32 v67, v6, v7
	s_waitcnt lgkmcnt(3)
	s_waitcnt lgkmcnt(1)
	s_waitcnt lgkmcnt(0)
	s_nop 0
	s_waitcnt vmcnt(8)
	s_waitcnt vmcnt(8)
	s_waitcnt lgkmcnt(3)
	s_waitcnt lgkmcnt(1)
	s_waitcnt lgkmcnt(0)
	s_waitcnt vmcnt(8)
	s_waitcnt vmcnt(8)
	ds_read_b128 v[0:3], v9 offset:10560
	ds_read_b128 v[4:7], v9 offset:10576
	ds_read_b128 v[26:29], v9 offset:8512
	ds_read_b128 v[30:33], v9 offset:8528
	ds_read_b128 v[34:37], v9 offset:9024
	ds_read_b128 v[38:41], v9 offset:9040
	s_mov_b64 exec, vcc
	v_lshlrev_b32_e32 v42, 16, v242
	v_and_b32_e32 v43, 0xffff0000, v242
	v_lshlrev_b32_e32 v44, 16, v243
	v_and_b32_e32 v45, 0xffff0000, v243
	s_waitcnt lgkmcnt(2)
	v_pk_fma_f32 v[0:1], v[26:27], v[42:43], v[0:1]
	v_pk_fma_f32 v[2:3], v[28:29], v[44:45], v[2:3]
	v_lshlrev_b32_e32 v46, 16, v244
	v_and_b32_e32 v47, 0xffff0000, v244
	v_lshlrev_b32_e32 v80, 16, v245
	v_and_b32_e32 v81, 0xffff0000, v245
	v_pk_fma_f32 v[4:5], v[30:31], v[46:47], v[4:5]
	v_pk_fma_f32 v[6:7], v[32:33], v[80:81], v[6:7]
	s_mov_b64 exec, -1
	ds_read_b128 v[26:29], v9 offset:9536
	ds_read_b128 v[30:33], v9 offset:9552
	s_mov_b64 exec, s[0:1]
	v_lshlrev_b32_e32 v42, 16, v246
	v_and_b32_e32 v43, 0xffff0000, v246
	v_lshlrev_b32_e32 v44, 16, v247
	v_and_b32_e32 v45, 0xffff0000, v247
	s_waitcnt lgkmcnt(2)
	v_pk_fma_f32 v[0:1], v[34:35], v[42:43], v[0:1]
	v_pk_fma_f32 v[2:3], v[36:37], v[44:45], v[2:3]
	v_lshlrev_b32_e32 v46, 16, v248
	v_and_b32_e32 v47, 0xffff0000, v248
	v_lshlrev_b32_e32 v80, 16, v249
	v_and_b32_e32 v81, 0xffff0000, v249
	v_pk_fma_f32 v[4:5], v[38:39], v[46:47], v[4:5]
	v_pk_fma_f32 v[6:7], v[40:41], v[80:81], v[6:7]
	s_mov_b64 exec, -1
	ds_read_b128 v[34:37], v9 offset:10048
	ds_read_b128 v[38:41], v9 offset:10064
	v_lshlrev_b32_e32 v42, 16, v252
	v_and_b32_e32 v43, 0xffff0000, v252
	v_lshlrev_b32_e32 v44, 16, v253
	v_and_b32_e32 v45, 0xffff0000, v253
	s_waitcnt lgkmcnt(2)
	v_pk_fma_f32 v[0:1], v[26:27], v[42:43], v[0:1]
	v_pk_fma_f32 v[2:3], v[28:29], v[44:45], v[2:3]
	v_lshlrev_b32_e32 v46, 16, v254
	v_and_b32_e32 v47, 0xffff0000, v254
	v_lshlrev_b32_e32 v80, 16, v255
	v_and_b32_e32 v81, 0xffff0000, v255
	v_pk_fma_f32 v[4:5], v[30:31], v[46:47], v[4:5]
	v_pk_fma_f32 v[6:7], v[32:33], v[80:81], v[6:7]
	s_mov_b64 exec, s[4:5]
	v_lshlrev_b32_e32 v42, 16, v168
	v_and_b32_e32 v43, 0xffff0000, v168
	v_lshlrev_b32_e32 v44, 16, v169
	v_and_b32_e32 v45, 0xffff0000, v169
	s_waitcnt lgkmcnt(0)
	v_pk_fma_f32 v[0:1], v[34:35], v[42:43], v[0:1]
	v_pk_fma_f32 v[2:3], v[36:37], v[44:45], v[2:3]
	v_lshlrev_b32_e32 v46, 16, v170
	v_and_b32_e32 v47, 0xffff0000, v170
	v_lshlrev_b32_e32 v80, 16, v171
	v_and_b32_e32 v81, 0xffff0000, v171
	v_pk_fma_f32 v[4:5], v[38:39], v[46:47], v[4:5]
	v_pk_fma_f32 v[6:7], v[40:41], v[80:81], v[6:7]
	s_mov_b64 exec, -1
	v_cvt_pk_bf16_f32 v68, v0, v1
	v_cvt_pk_bf16_f32 v69, v2, v3
	v_cvt_pk_bf16_f32 v70, v4, v5
	v_cvt_pk_bf16_f32 v71, v6, v7
	s_waitcnt lgkmcnt(3)
	s_waitcnt lgkmcnt(1)
	s_waitcnt lgkmcnt(0)
	s_nop 0
	s_waitcnt vmcnt(4)
	s_waitcnt vmcnt(4)
	s_waitcnt lgkmcnt(3)
	s_waitcnt lgkmcnt(1)
	s_waitcnt lgkmcnt(0)
	s_waitcnt vmcnt(4)
	s_waitcnt vmcnt(4)
	ds_read_b128 v[0:3], v9 offset:10624
	ds_read_b128 v[4:7], v9 offset:10640
	ds_read_b128 v[26:29], v9 offset:8576
	ds_read_b128 v[30:33], v9 offset:8592
	ds_read_b128 v[34:37], v9 offset:9088
	ds_read_b128 v[38:41], v9 offset:9104
	s_mov_b64 exec, vcc
	v_lshlrev_b32_e32 v42, 16, v178
	v_and_b32_e32 v43, 0xffff0000, v178
	v_lshlrev_b32_e32 v44, 16, v179
	v_and_b32_e32 v45, 0xffff0000, v179
	s_waitcnt lgkmcnt(2)
	v_pk_fma_f32 v[0:1], v[26:27], v[42:43], v[0:1]
	v_pk_fma_f32 v[2:3], v[28:29], v[44:45], v[2:3]
	v_lshlrev_b32_e32 v46, 16, v180
	v_and_b32_e32 v47, 0xffff0000, v180
	v_lshlrev_b32_e32 v80, 16, v181
	v_and_b32_e32 v81, 0xffff0000, v181
	v_pk_fma_f32 v[4:5], v[30:31], v[46:47], v[4:5]
	v_pk_fma_f32 v[6:7], v[32:33], v[80:81], v[6:7]
	s_mov_b64 exec, -1
	ds_read_b128 v[26:29], v9 offset:9600
	ds_read_b128 v[30:33], v9 offset:9616
	s_mov_b64 exec, s[0:1]
	v_lshlrev_b32_e32 v42, 16, v182
	v_and_b32_e32 v43, 0xffff0000, v182
	v_lshlrev_b32_e32 v44, 16, v183
	v_and_b32_e32 v45, 0xffff0000, v183
	s_waitcnt lgkmcnt(2)
	v_pk_fma_f32 v[0:1], v[34:35], v[42:43], v[0:1]
	v_pk_fma_f32 v[2:3], v[36:37], v[44:45], v[2:3]
	v_lshlrev_b32_e32 v46, 16, v184
	v_and_b32_e32 v47, 0xffff0000, v184
	v_lshlrev_b32_e32 v80, 16, v185
	v_and_b32_e32 v81, 0xffff0000, v185
	v_pk_fma_f32 v[4:5], v[38:39], v[46:47], v[4:5]
	v_pk_fma_f32 v[6:7], v[40:41], v[80:81], v[6:7]
	s_mov_b64 exec, -1
	ds_read_b128 v[34:37], v9 offset:10112
	ds_read_b128 v[38:41], v9 offset:10128
	v_lshlrev_b32_e32 v42, 16, v186
	v_and_b32_e32 v43, 0xffff0000, v186
	v_lshlrev_b32_e32 v44, 16, v187
	v_and_b32_e32 v45, 0xffff0000, v187
	s_waitcnt lgkmcnt(2)
	v_pk_fma_f32 v[0:1], v[26:27], v[42:43], v[0:1]
	v_pk_fma_f32 v[2:3], v[28:29], v[44:45], v[2:3]
	v_lshlrev_b32_e32 v46, 16, v188
	v_and_b32_e32 v47, 0xffff0000, v188
	v_lshlrev_b32_e32 v80, 16, v189
	v_and_b32_e32 v81, 0xffff0000, v189
	v_pk_fma_f32 v[4:5], v[30:31], v[46:47], v[4:5]
	v_pk_fma_f32 v[6:7], v[32:33], v[80:81], v[6:7]
	s_mov_b64 exec, s[4:5]
	v_lshlrev_b32_e32 v42, 16, v190
	v_and_b32_e32 v43, 0xffff0000, v190
	v_lshlrev_b32_e32 v44, 16, v191
	v_and_b32_e32 v45, 0xffff0000, v191
	s_waitcnt lgkmcnt(0)
	v_pk_fma_f32 v[0:1], v[34:35], v[42:43], v[0:1]
	v_pk_fma_f32 v[2:3], v[36:37], v[44:45], v[2:3]
	v_lshlrev_b32_e32 v46, 16, v192
	v_and_b32_e32 v47, 0xffff0000, v192
	v_lshlrev_b32_e32 v80, 16, v193
	v_and_b32_e32 v81, 0xffff0000, v193
	v_pk_fma_f32 v[4:5], v[38:39], v[46:47], v[4:5]
	v_pk_fma_f32 v[6:7], v[40:41], v[80:81], v[6:7]
	s_mov_b64 exec, -1
	v_cvt_pk_bf16_f32 v72, v0, v1
	v_cvt_pk_bf16_f32 v73, v2, v3
	v_cvt_pk_bf16_f32 v74, v4, v5
	v_cvt_pk_bf16_f32 v75, v6, v7
	s_waitcnt lgkmcnt(3)
	s_waitcnt lgkmcnt(1)
	s_waitcnt lgkmcnt(0)
	v_lshlrev_b32_e32 v38, 3, v93
	s_nop 0
	s_nop 0
	v_or_b32_e32 v39, 16, v38
	s_waitcnt vmcnt(0)
	s_waitcnt vmcnt(0)
	s_waitcnt lgkmcnt(3)
	s_waitcnt lgkmcnt(1)
	s_waitcnt lgkmcnt(0)
	s_waitcnt vmcnt(0)
	s_waitcnt vmcnt(0)
	ds_read_b128 v[0:3], v9 offset:10688
	ds_read_b128 v[4:7], v9 offset:10704
	ds_read_b128 v[26:29], v9 offset:8640
	ds_read_b128 v[30:33], v9 offset:8656
	ds_read_b128 v[34:37], v9 offset:9152
	ds_read_b128 v[40:43], v9 offset:9168
	s_mov_b64 exec, vcc
	v_lshlrev_b32_e32 v44, 16, v194
	v_and_b32_e32 v45, 0xffff0000, v194
	v_lshlrev_b32_e32 v46, 16, v195
	v_and_b32_e32 v47, 0xffff0000, v195
	s_waitcnt lgkmcnt(2)
	v_pk_fma_f32 v[0:1], v[26:27], v[44:45], v[0:1]
	v_pk_fma_f32 v[2:3], v[28:29], v[46:47], v[2:3]
	v_lshlrev_b32_e32 v80, 16, v196
	v_and_b32_e32 v81, 0xffff0000, v196
	v_lshlrev_b32_e32 v82, 16, v197
	v_and_b32_e32 v83, 0xffff0000, v197
	v_pk_fma_f32 v[4:5], v[30:31], v[80:81], v[4:5]
	v_pk_fma_f32 v[6:7], v[32:33], v[82:83], v[6:7]
	s_mov_b64 exec, -1
	ds_read_b128 v[26:29], v9 offset:9664
	ds_read_b128 v[30:33], v9 offset:9680
	s_mov_b64 exec, s[0:1]
	v_lshlrev_b32_e32 v44, 16, v198
	v_and_b32_e32 v45, 0xffff0000, v198
	v_lshlrev_b32_e32 v46, 16, v199
	v_and_b32_e32 v47, 0xffff0000, v199
	s_waitcnt lgkmcnt(2)
	v_pk_fma_f32 v[0:1], v[34:35], v[44:45], v[0:1]
	v_pk_fma_f32 v[2:3], v[36:37], v[46:47], v[2:3]
	v_lshlrev_b32_e32 v80, 16, v200
	v_and_b32_e32 v81, 0xffff0000, v200
	v_lshlrev_b32_e32 v82, 16, v201
	v_and_b32_e32 v83, 0xffff0000, v201
	v_pk_fma_f32 v[4:5], v[40:41], v[80:81], v[4:5]
	v_pk_fma_f32 v[6:7], v[42:43], v[82:83], v[6:7]
	s_mov_b64 exec, -1
	ds_read_b128 v[34:37], v9 offset:10176
	ds_read_b128 v[40:43], v9 offset:10192
	v_lshlrev_b32_e32 v44, 16, v202
	v_and_b32_e32 v45, 0xffff0000, v202
	v_lshlrev_b32_e32 v46, 16, v203
	v_and_b32_e32 v47, 0xffff0000, v203
	s_waitcnt lgkmcnt(2)
	v_pk_fma_f32 v[0:1], v[26:27], v[44:45], v[0:1]
	v_pk_fma_f32 v[2:3], v[28:29], v[46:47], v[2:3]
	v_lshlrev_b32_e32 v80, 16, v204
	v_and_b32_e32 v81, 0xffff0000, v204
	v_lshlrev_b32_e32 v82, 16, v205
	v_and_b32_e32 v83, 0xffff0000, v205
	v_pk_fma_f32 v[4:5], v[30:31], v[80:81], v[4:5]
	v_pk_fma_f32 v[6:7], v[32:33], v[82:83], v[6:7]
	s_mov_b64 exec, s[4:5]
	v_lshlrev_b32_e32 v44, 16, v206
	v_and_b32_e32 v45, 0xffff0000, v206
	v_lshlrev_b32_e32 v46, 16, v207
	v_and_b32_e32 v47, 0xffff0000, v207
	s_waitcnt lgkmcnt(0)
	v_pk_fma_f32 v[0:1], v[34:35], v[44:45], v[0:1]
	v_pk_fma_f32 v[2:3], v[36:37], v[46:47], v[2:3]
	v_lshlrev_b32_e32 v80, 16, v208
	v_and_b32_e32 v81, 0xffff0000, v208
	v_lshlrev_b32_e32 v82, 16, v209
	v_and_b32_e32 v83, 0xffff0000, v209
	v_pk_fma_f32 v[4:5], v[40:41], v[80:81], v[4:5]
	v_pk_fma_f32 v[6:7], v[42:43], v[82:83], v[6:7]
	s_mov_b64 exec, -1
	v_cvt_pk_bf16_f32 v76, v0, v1
	v_cvt_pk_bf16_f32 v77, v2, v3
	v_cvt_pk_bf16_f32 v78, v4, v5
	v_cvt_pk_bf16_f32 v79, v6, v7
	s_waitcnt lgkmcnt(3)
	s_waitcnt lgkmcnt(1)
	s_waitcnt lgkmcnt(0)
	v_cmp_eq_u32_e32 vcc, v38, v94
	v_or_b32_e32 v2, 1, v38
	v_cndmask_b32_e32 v0, 0, v134, vcc
	v_or_b32_e32 v1, 2, v38
	v_cmp_eq_u32_e32 vcc, v2, v94
	v_or_b32_e32 v4, 3, v38
	v_or_b32_e32 v3, 4, v38
	v_cndmask_b32_e32 v2, 0, v134, vcc
	v_cmp_eq_u32_e32 vcc, v1, v94
	v_or_b32_e32 v5, 6, v38
	v_or_b32_e32 v6, 5, v38
	v_cndmask_b32_e32 v1, 0, v134, vcc
	v_cmp_eq_u32_e32 vcc, v4, v94
	v_or_b32_e32 v7, 7, v38
	v_or_b32_e32 v11, 17, v38
	v_cndmask_b32_e32 v4, 0, v134, vcc
	v_cmp_eq_u32_e32 vcc, v3, v94
	v_or_b32_e32 v10, 18, v38
	v_or_b32_e32 v13, 19, v38
	v_cndmask_b32_e32 v3, 0, v134, vcc
	v_cmp_eq_u32_e32 vcc, v5, v94
	v_or_b32_e32 v12, 20, v38
	v_or_b32_e32 v14, 22, v38
	v_cndmask_b32_e32 v5, 0, v134, vcc
	v_cmp_eq_u32_e32 vcc, v6, v94
	v_or_b32_e32 v15, 21, v38
	v_or_b32_e32 v16, 23, v38
	v_cndmask_b32_e32 v6, 0, v134, vcc
	v_cmp_eq_u32_e32 vcc, v7, v94
	v_and_b32_e32 v18, 64, v132
	v_xor_b32_e32 v17, 32, v132
	v_cndmask_b32_e32 v7, 0, v134, vcc
	v_cmp_eq_u32_e32 vcc, v39, v94
	v_add_u32_e32 v18, 64, v18
	s_lshl_b32 s4, s62, 8
	v_cndmask_b32_e32 v9, 0, v134, vcc
	v_cmp_eq_u32_e32 vcc, v11, v94
	s_add_i32 s4, s4, 16
	v_cmp_eq_u32_e64 s[0:1], 0, v93
	v_cndmask_b32_e32 v11, 0, v134, vcc
	v_cmp_eq_u32_e32 vcc, v10, v94
	v_lshl_add_u32 v139, v94, 3, s4
	v_perm_b32 v82, v6, v3, s83
	v_cndmask_b32_e32 v10, 0, v134, vcc
	v_cmp_eq_u32_e32 vcc, v13, v94
	v_perm_b32 v81, v4, v1, s83
	v_perm_b32 v83, v7, v5, s83
	v_cndmask_b32_e32 v13, 0, v134, vcc
	v_cmp_eq_u32_e32 vcc, v12, v94
	v_perm_b32 v80, v2, v0, s83
	v_perm_b32 v85, v13, v10, s83
	v_cndmask_b32_e32 v12, 0, v134, vcc
	v_cmp_eq_u32_e32 vcc, v14, v94
	v_perm_b32 v84, v11, v9, s83
	s_nop 0
	v_cndmask_b32_e32 v14, 0, v134, vcc
	v_cmp_eq_u32_e32 vcc, v15, v94
	s_nop 1
	v_cndmask_b32_e32 v15, 0, v134, vcc
	v_cmp_eq_u32_e32 vcc, v16, v94
	v_perm_b32 v86, v15, v12, s83
	s_nop 0
	v_cndmask_b32_e32 v16, 0, v134, vcc
	v_cmp_lt_i32_e32 vcc, v17, v18
	v_perm_b32 v87, v16, v14, s83
	s_nop 0
	v_cndmask_b32_e32 v17, v132, v17, vcc
	v_lshlrev_b32_e32 v140, 2, v17
	v_lshlrev_b32_e32 v175, 2, v91
	global_load_dword v172, v175, s[42:43]
	global_load_dword v173, v175, s[36:37]
	global_load_dword v174, v175, s[40:41]
	s_setprio 1
	v_xad_u32 v148, v88, v8, v95
	ds_read_b128 v[0:3], v148 offset:16384
	ds_read_b128 v[4:7], v148 offset:49152
	s_waitcnt lgkmcnt(1)
	v_mfma_f32_32x32x16_bf16 v[32:47], v[48:51], v[0:3], 0
	v_or_b32_e32 v0, 32, v88
	v_xad_u32 v150, v0, v8, v95
	s_waitcnt lgkmcnt(0)
	v_mfma_f32_32x32x16_bf16 v[16:31], v[48:51], v[4:7], 0
	ds_read_b128 v[0:3], v150 offset:16384
	ds_read_b128 v[4:7], v150 offset:49152
	s_waitcnt lgkmcnt(1)
	v_mfma_f32_32x32x16_bf16 v[32:47], v[52:55], v[0:3], v[32:47]
	v_or_b32_e32 v0, 64, v88
	v_xad_u32 v145, v0, v8, v95
	s_waitcnt lgkmcnt(0)
	v_mfma_f32_32x32x16_bf16 v[16:31], v[52:55], v[4:7], v[16:31]
	ds_read_b128 v[0:3], v145 offset:16384
	ds_read_b128 v[4:7], v145 offset:49152
	s_waitcnt lgkmcnt(1)
	v_mfma_f32_32x32x16_bf16 v[32:47], v[56:59], v[0:3], v[32:47]
	v_or_b32_e32 v0, 0x60, v88
	v_xad_u32 v149, v0, v8, v95
	s_waitcnt lgkmcnt(0)
	v_mfma_f32_32x32x16_bf16 v[16:31], v[56:59], v[4:7], v[16:31]
	ds_read_b128 v[0:3], v149 offset:16384
	ds_read_b128 v[4:7], v149 offset:49152
	s_waitcnt lgkmcnt(1)
	v_mfma_f32_32x32x16_bf16 v[32:47], v[60:63], v[0:3], v[32:47]
	v_or_b32_e32 v0, 0x80, v88
	v_xad_u32 v144, v0, v8, v95
	s_waitcnt lgkmcnt(0)
	v_mfma_f32_32x32x16_bf16 v[16:31], v[60:63], v[4:7], v[16:31]
	ds_read_b128 v[0:3], v144 offset:16384
	ds_read_b128 v[4:7], v144 offset:49152
	s_waitcnt lgkmcnt(1)
	v_mfma_f32_32x32x16_bf16 v[32:47], v[64:67], v[0:3], v[32:47]
	v_or_b32_e32 v0, 0xa0, v88
	v_xad_u32 v147, v0, v8, v95
	s_waitcnt lgkmcnt(0)
	v_mfma_f32_32x32x16_bf16 v[16:31], v[64:67], v[4:7], v[16:31]
	ds_read_b128 v[0:3], v147 offset:16384
	ds_read_b128 v[4:7], v147 offset:49152
	s_waitcnt lgkmcnt(1)
	v_mfma_f32_32x32x16_bf16 v[32:47], v[68:71], v[0:3], v[32:47]
	v_or_b32_e32 v0, 0xc0, v88
	v_xad_u32 v143, v0, v8, v95
	s_waitcnt lgkmcnt(0)
	v_mfma_f32_32x32x16_bf16 v[16:31], v[68:71], v[4:7], v[16:31]
	ds_read_b128 v[0:3], v143 offset:16384
	ds_read_b128 v[4:7], v143 offset:49152
	s_waitcnt lgkmcnt(1)
	v_mfma_f32_32x32x16_bf16 v[32:47], v[72:75], v[0:3], v[32:47]
	v_or_b32_e32 v0, 0xe0, v88
	v_xad_u32 v146, v0, v8, v95
	s_waitcnt lgkmcnt(0)
	v_mfma_f32_32x32x16_bf16 v[16:31], v[72:75], v[4:7], v[16:31]
	ds_read_b128 v[0:3], v146 offset:16384
	ds_read_b128 v[4:7], v146 offset:49152
	s_waitcnt lgkmcnt(1)
	v_mfma_f32_32x32x16_bf16 v[32:47], v[76:79], v[0:3], v[32:47]
	s_waitcnt lgkmcnt(0)
	v_mfma_f32_32x32x16_bf16 v[16:31], v[76:79], v[4:7], v[16:31]
	v_mfma_f32_32x32x16_bf16 v[0:15], v[48:51], v[80:83], 0
	v_mfma_f32_32x32x16_bf16 v[0:15], v[52:55], v[84:87], v[0:15]
	s_setprio 0
	v_lshlrev_b32_e32 v88, 2, v91
	s_waitcnt vmcnt(0)
	ds_read_b32 v251, v167
	v_mul_f32_e32 v97, 0xbfb8aa3b, v173
	v_mul_f32_e32 v96, 0xbfb8aa3b, v174
	v_fmamk_f32 v32, v32, 0xbfb8aa3b, v97
	v_fmamk_f32 v34, v34, 0xbfb8aa3b, v97
	v_fmamk_f32 v33, v33, 0xbfb8aa3b, v97
	v_fmamk_f32 v35, v35, 0xbfb8aa3b, v97
	v_fmamk_f32 v16, v16, 0xbfb8aa3b, v96
	v_fmamk_f32 v17, v17, 0xbfb8aa3b, v96
	v_exp_f32_e32 v32, v32
	v_exp_f32_e32 v34, v34
	v_exp_f32_e32 v33, v33
	v_exp_f32_e32 v107, v35
	v_exp_f32_e32 v91, v16
	v_exp_f32_e32 v98, v17
	v_add_f32_e32 v32, 1.0, v32
	v_add_f32_e32 v108, 1.0, v34
	v_add_f32_e32 v33, 1.0, v33
	v_rcp_f32_e32 v109, v32
	v_rcp_f32_e32 v111, v33
	v_add_f32_e32 v91, 1.0, v91
	v_rcp_f32_e32 v110, v91
	v_add_f32_e32 v98, 1.0, v98
	v_rcp_f32_e32 v112, v98
	v_fmamk_f32 v18, v18, 0xbfb8aa3b, v96
	v_exp_f32_e32 v18, v18
	v_fmamk_f32 v20, v20, 0xbfb8aa3b, v96
	v_add_f32_e32 v18, 1.0, v18
	v_exp_f32_e32 v20, v20
	v_fmamk_f32 v19, v19, 0xbfb8aa3b, v96
	v_exp_f32_e32 v19, v19
	v_fmamk_f32 v21, v21, 0xbfb8aa3b, v96
	s_waitcnt lgkmcnt(0)
	v_mul_f32_e32 v33, 0x3fb8aa3b, v251
	v_mul_f32_e32 v16, v109, v33
	v_exp_f32_e32 v32, v16
	v_mul_f32_e32 v17, v111, v33
	v_exp_f32_e32 v34, v17
	v_rcp_f32_e32 v16, v108
	v_rcp_f32_e32 v17, v18
	v_fma_f32 v18, -v32, v32, 1.0
	v_sqrt_f32_e32 v18, v18
	v_mul_f32_e32 v16, v16, v33
	v_add_f32_e32 v19, 1.0, v19
	v_mul_f32_e32 v18, v110, v18
	v_mul_f32_e32 v18, v0, v18
	v_exp_f32_e32 v0, v16
	v_add_f32_e32 v16, 1.0, v107
	v_rcp_f32_e32 v16, v16
	v_rcp_f32_e32 v19, v19
	v_fma_f32 v91, -v0, v0, 1.0
	v_sqrt_f32_e32 v91, v91
	v_mul_f32_e32 v16, v16, v33
	v_exp_f32_e32 v98, v16
	v_fmamk_f32 v16, v36, 0xbfb8aa3b, v97
	v_exp_f32_e32 v16, v16
	v_mul_f32_e32 v91, v17, v91
	v_add_f32_e32 v17, 1.0, v20
	v_fma_f32 v36, -v98, v98, 1.0
	v_add_f32_e32 v16, 1.0, v16
	v_rcp_f32_e32 v16, v16
	v_sqrt_f32_e32 v36, v36
	v_rcp_f32_e32 v17, v17
	v_mul_f32_e32 v16, v16, v33
	v_exp_f32_e32 v20, v16
	v_fmamk_f32 v16, v37, 0xbfb8aa3b, v97
	v_exp_f32_e32 v16, v16
	v_mul_f32_e32 v36, v19, v36
	v_fma_f32 v19, -v20, v20, 1.0
	v_sqrt_f32_e32 v19, v19
	v_add_f32_e32 v16, 1.0, v16
	v_rcp_f32_e32 v16, v16
	v_exp_f32_e32 v21, v21
	v_mul_f32_e32 v17, v17, v19
	v_mul_f32_e32 v19, v4, v17
	v_mul_f32_e32 v16, v16, v33
	v_exp_f32_e32 v37, v16
	v_fmamk_f32 v16, v38, 0xbfb8aa3b, v97
	v_exp_f32_e32 v16, v16
	v_add_f32_e32 v4, 1.0, v21
	v_fmamk_f32 v21, v22, 0xbfb8aa3b, v96
	v_add_f32_e32 v16, 1.0, v16
	v_rcp_f32_e32 v16, v16
	v_fma_f32 v17, -v37, v37, 1.0
	v_exp_f32_e32 v21, v21
	v_rcp_f32_e32 v4, v4
	v_mul_f32_e32 v16, v16, v33
	v_sqrt_f32_e32 v17, v17
	v_exp_f32_e32 v38, v16
	v_add_f32_e32 v16, 1.0, v21
	v_fmamk_f32 v21, v39, 0xbfb8aa3b, v97
	v_mul_f32_e32 v4, v4, v17
	v_fma_f32 v17, -v38, v38, 1.0
	v_rcp_f32_e32 v16, v16
	v_sqrt_f32_e32 v17, v17
	v_exp_f32_e32 v21, v21
	v_fmamk_f32 v22, v23, 0xbfb8aa3b, v96
	v_mul_f32_e32 v23, v16, v17
	v_add_f32_e32 v16, 1.0, v21
	v_rcp_f32_e32 v16, v16
	v_fmamk_f32 v21, v40, 0xbfb8aa3b, v97
	v_exp_f32_e32 v21, v21
	v_mul_f32_e32 v16, v16, v33
	v_exp_f32_e32 v39, v16
	v_add_f32_e32 v16, 1.0, v21
	v_rcp_f32_e32 v16, v16
	v_exp_f32_e32 v22, v22
	v_fmamk_f32 v21, v24, 0xbfb8aa3b, v96
	v_mul_f32_e32 v16, v16, v33
	v_add_f32_e32 v17, 1.0, v22
	v_fma_f32 v22, -v39, v39, 1.0
	v_sqrt_f32_e32 v24, v22
	v_exp_f32_e32 v22, v16
	v_fmamk_f32 v16, v41, 0xbfb8aa3b, v97
	v_exp_f32_e32 v16, v16
	v_exp_f32_e32 v21, v21
	v_fma_f32 v40, -v22, v22, 1.0
	v_rcp_f32_e32 v17, v17
	v_add_f32_e32 v16, 1.0, v16
	v_rcp_f32_e32 v16, v16
	v_add_f32_e32 v21, 1.0, v21
	v_rcp_f32_e32 v21, v21
	v_sqrt_f32_e32 v40, v40
	v_mul_f32_e32 v16, v16, v33
	v_mul_f32_e32 v24, v17, v24
	v_mul_f32_e32 v17, v21, v40
	v_exp_f32_e32 v40, v16
	v_fmamk_f32 v16, v42, 0xbfb8aa3b, v97
	v_fmamk_f32 v25, v25, 0xbfb8aa3b, v96
	v_exp_f32_e32 v16, v16
	v_exp_f32_e32 v25, v25
	v_fma_f32 v35, -v34, v34, 1.0
	v_sqrt_f32_e32 v35, v35
	v_add_f32_e32 v16, 1.0, v16
	v_add_f32_e32 v21, 1.0, v25
	v_rcp_f32_e32 v16, v16
	v_rcp_f32_e32 v25, v21
	v_fma_f32 v21, -v40, v40, 1.0
	v_sqrt_f32_e32 v41, v21
	v_fmamk_f32 v21, v26, 0xbfb8aa3b, v96
	v_mul_f32_e32 v16, v16, v33
	v_exp_f32_e32 v26, v21
	v_mul_f32_e32 v21, v8, v17
	v_mul_f32_e32 v8, v25, v41
	v_exp_f32_e32 v41, v16
	v_fmamk_f32 v16, v43, 0xbfb8aa3b, v97
	v_exp_f32_e32 v16, v16
	v_add_f32_e32 v17, 1.0, v26
	v_fma_f32 v25, -v41, v41, 1.0
	v_fmamk_f32 v26, v27, 0xbfb8aa3b, v96
	v_add_f32_e32 v16, 1.0, v16
	v_rcp_f32_e32 v16, v16
	v_rcp_f32_e32 v17, v17
	v_sqrt_f32_e32 v25, v25
	v_mul_f32_e32 v16, v16, v33
	v_exp_f32_e32 v26, v26
	v_exp_f32_e32 v99, v16
	v_mul_f32_e32 v100, v17, v25
	v_fmamk_f32 v25, v44, 0xbfb8aa3b, v97
	v_add_f32_e32 v16, 1.0, v26
	v_fmamk_f32 v26, v28, 0xbfb8aa3b, v96
	v_fma_f32 v17, -v99, v99, 1.0
	v_exp_f32_e32 v25, v25
	v_rcp_f32_e32 v16, v16
	v_sqrt_f32_e32 v17, v17
	v_exp_f32_e32 v26, v26
	v_add_f32_e32 v25, 1.0, v25
	v_rcp_f32_e32 v25, v25
	v_mul_f32_e32 v101, v16, v17
	v_add_f32_e32 v16, 1.0, v26
	v_fmamk_f32 v26, v29, 0xbfb8aa3b, v96
	v_exp_f32_e32 v26, v26
	v_rcp_f32_e32 v17, v16
	v_mul_f32_e32 v16, v25, v33
	v_fmamk_f32 v25, v45, 0xbfb8aa3b, v97
	v_exp_f32_e32 v25, v25
	v_add_f32_e32 v26, 1.0, v26
	v_rcp_f32_e32 v42, v26
	v_fmamk_f32 v26, v46, 0xbfb8aa3b, v97
	v_exp_f32_e32 v26, v26
	v_add_f32_e32 v25, 1.0, v25
	v_rcp_f32_e32 v25, v25
	v_fmamk_f32 v27, v30, 0xbfb8aa3b, v96
	v_exp_f32_e32 v27, v27
	v_add_f32_e32 v26, 1.0, v26
	v_rcp_f32_e32 v26, v26
	v_mul_f32_e32 v25, v25, v33
	v_exp_f32_e32 v43, v25
	v_add_f32_e32 v25, 1.0, v27
	v_rcp_f32_e32 v44, v25
	v_mul_f32_e32 v25, v26, v33
	v_fmamk_f32 v26, v47, 0xbfb8aa3b, v97
	v_exp_f32_e32 v26, v26
	v_fmamk_f32 v27, v31, 0xbfb8aa3b, v96
	v_exp_f32_e32 v27, v27
	v_add_f32_e32 v26, 1.0, v26
	v_rcp_f32_e32 v26, v26
	v_exp_f32_e32 v16, v16
	v_fmac_f32_e32 v18, 0, v32
	v_mul_f32_e32 v35, v112, v35
	v_exp_f32_e32 v45, v25
	v_add_f32_e32 v25, 1.0, v27
	v_mul_f32_e32 v31, v34, v18
	v_rcp_f32_e32 v46, v25
	v_mul_f32_e32 v25, v26, v33
	v_fmac_f32_e32 v31, v1, v35
	v_mul_f32_e32 v33, v32, v34
	v_mul_f32_e32 v30, v0, v31
	v_mul_f32_e32 v34, v0, v33
	v_fma_f32 v0, -v16, v16, 1.0
	v_sqrt_f32_e32 v1, v0
	v_fmac_f32_e32 v30, v2, v91
	v_fmac_f32_e32 v21, 0, v22
	v_fma_f32 v2, -v43, v43, 1.0
	v_exp_f32_e32 v47, v25
	v_mul_f32_e32 v25, v40, v21
	v_mov_b32_e32 v0, v89
	v_sqrt_f32_e32 v2, v2
	v_fmac_f32_e32 v25, v9, v8
	v_pk_mul_f32 v[8:9], v[16:17], v[0:1]
	v_mul_f32_e32 v29, v98, v30
	v_fmac_f32_e32 v19, 0, v20
	v_fmac_f32_e32 v8, v12, v9
	v_fmac_f32_e32 v29, v3, v36
	v_mul_f32_e32 v28, v37, v19
	v_mov_b32_e32 v3, v8
	v_fmac_f32_e32 v28, v5, v4
	v_pk_mul_f32 v[4:5], v[42:43], v[2:3]
	v_fma_f32 v0, -v45, v45, 1.0
	v_fmac_f32_e32 v5, v13, v4
	v_sqrt_f32_e32 v4, v0
	v_mul_f32_e32 v27, v38, v28
	v_fmac_f32_e32 v27, v6, v23
	v_mul_f32_e32 v26, v39, v27
	v_fmac_f32_e32 v26, v7, v24
	v_pk_mul_f32 v[6:7], v[44:45], v[4:5]
	v_fma_f32 v0, -v47, v47, 1.0
	v_fmac_f32_e32 v7, v14, v6
	v_sqrt_f32_e32 v6, v0
	ds_bpermute_b32 v0, v140, v29
	v_mul_f32_e32 v24, v41, v25
	v_mul_f32_e32 v35, v98, v34
	v_mul_f32_e32 v36, v20, v37
	v_fmac_f32_e32 v24, v10, v100
	v_mul_f32_e32 v37, v38, v36
	v_mul_f32_e32 v23, v99, v24
	ds_bpermute_b32 v13, v140, v35
	v_mul_f32_e32 v38, v39, v37
	v_fmac_f32_e32 v23, v11, v101
	v_pk_mul_f32 v[10:11], v[46:47], v[6:7]
	s_waitcnt lgkmcnt(1)
	v_cndmask_b32_e64 v14, v29, v0, s[0:1]
	v_fmac_f32_e32 v11, v15, v10
	v_cndmask_b32_e64 v10, v0, v29, s[0:1]
	ds_bpermute_b32 v0, v140, v38
	ds_bpermute_b32 v3, v140, v26
	v_mul_f32_e32 v39, v22, v40
	v_mul_f32_e32 v40, v41, v39
	s_waitcnt lgkmcnt(2)
	v_cndmask_b32_e64 v1, v13, v35, s[0:1]
	v_mul_f32_e32 v12, v99, v40
	v_mul_f32_e32 v9, v16, v43
	v_cndmask_b32_e64 v2, v35, v13, s[0:1]
	v_fmac_f32_e32 v10, 0, v1
	v_mul_f32_e32 v4, v45, v9
	v_mul_f32_e32 v15, v35, v13
	v_fmac_f32_e32 v14, v2, v10
	s_waitcnt lgkmcnt(1)
	v_cndmask_b32_e64 v1, v0, v38, s[0:1]
	s_waitcnt lgkmcnt(0)
	v_cndmask_b32_e64 v17, v3, v26, s[0:1]
	v_cndmask_b32_e64 v41, v26, v3, s[0:1]
	ds_bpermute_b32 v2, v140, v12
	ds_bpermute_b32 v3, v140, v23
	v_mul_f32_e32 v6, v47, v4
	v_cndmask_b32_e64 v0, v38, v0, s[0:1]
	v_mul_f32_e32 v42, v15, v1
	v_fmac_f32_e32 v17, v1, v14
	v_mul_f32_e32 v43, v0, v42
	v_fmac_f32_e32 v41, v0, v17
	ds_bpermute_b32 v1, v140, v6
	ds_bpermute_b32 v0, v140, v11
	s_waitcnt lgkmcnt(3)
	v_cndmask_b32_e64 v47, v2, v12, s[0:1]
	s_waitcnt lgkmcnt(2)
	v_cndmask_b32_e64 v44, v3, v23, s[0:1]
	v_cndmask_b32_e64 v2, v12, v2, s[0:1]
	v_cndmask_b32_e64 v45, v23, v3, s[0:1]
	v_mul_f32_e32 v46, v47, v43
	v_fmac_f32_e32 v44, v47, v41
	v_mul_f32_e32 v47, v2, v46
	v_fmac_f32_e32 v45, v2, v44
	s_waitcnt lgkmcnt(1)
	v_cndmask_b32_e64 v2, v1, v6, s[0:1]
	s_waitcnt lgkmcnt(0)
	v_cndmask_b32_e64 v91, v0, v11, s[0:1]
	v_mul_f32_e32 v96, v2, v47
	v_fmac_f32_e32 v91, v2, v45
	s_and_saveexec_b64 s[4:5], s[0:1]
	v_mul_f32_e32 v3, v91, v1
	v_mul_f32_e32 v2, v96, v1
	v_add_f32_e32 v3, v3, v0
	ds_write_b64 v139, v[2:3]
	s_or_b64 exec, exec, s[4:5]
	s_cmp_gt_i32 s62, 0
	s_cselect_b64 s[12:13], -1, 0
	s_cmp_lt_i32 s62, 1
	v_mul_i32_i24_e32 v141, 0xffffff08, v94
	s_waitcnt lgkmcnt(0)
	s_barrier
	s_cbranch_scc1 .LBB0_327
	s_cmp_lt_u32 s62, 8
	s_cbranch_scc1 .LBB0_328
	v_add_u32_e32 v95, v95, v141
	s_and_b32 s4, s62, 0x7ffffff8
	v_mov_b32_e32 v0, 1.0
	v_mov_b32_e32 v3, 0
	s_mov_b32 s5, 0
